# GEMM K-loops: removed the s_setprio 0/1 pair in the middle of each 32-MFMA block (priority stays 1 across the block)
# speedup vs baseline: 1.0055x; 1.0055x over previous
; #define PG8_STAGE(bufoff, gbase, voff) do { _Pragma("unroll") for (int _i = 0; _i < 2; ++_i) \
;         __builtin_amdgcn_global_load_lds((const unsigned*)((const char*)(gbase) + (voff)[_i]), (PG8_LAS unsigned*)(lds + (bufoff) + ldsw + _i * 8192), 16, 0, 0); } while (0)
; #define PG8_LDA(dst, b, h) do { _Pragma("unroll") for (int m = 0; m < 4; ++m) _Pragma("unroll") for (int k = 0; k < 2; ++k) dst[m][k] = *(const PG8_LAS bf16x8*)(lds + PG8_SA(b, h) + aoff + m * 2048 + k * 1024); } while (0)
; #define PG8_LDB(dst, b, h) do { _Pragma("unroll") for (int n = 0; n < 2; ++n) _Pragma("unroll") for (int k = 0; k < 2; ++k) dst[n][k] = *(const PG8_LAS bf16x8*)(lds + PG8_SB(b, h) + boff + n * 2048 + k * 1024); } while (0)
; #define PG8_MMA(ai, bj, At, Bt) do { __builtin_amdgcn_s_setprio(1); _Pragma("unroll") for (int m = 0; m < 4; ++m) _Pragma("unroll") for (int n = 0; n < 2; ++n) _Pragma("unroll") for (int k = 0; k < 2; ++k) \
;         acc[ai][bj][m][n] = __builtin_amdgcn_mfma_f32_16x16x32_bf16(Bt[n][k], At[m][k], acc[ai][bj][m][n], 0, 0, 0); __builtin_amdgcn_s_setprio(0); } while (0)
; #define PG8_WAIT_V(n) asm volatile("s_waitcnt vmcnt(" #n ")" ::: "memory")
; #define PG8_WAIT_L(n) asm volatile("s_waitcnt lgkmcnt(" #n ")" ::: "memory")
; template <class Epi, class Sched, bool ALIGN_EPI = false, bool SP2 = false>
; __device__ __forceinline__ void gemm_phase(PG8_LAS unsigned char* lds, const Gemm g, const Sched& S, const Epi& E, int tid_in) {
;     ...
;             const bool last = (t == nt - 2);
;             const char* a1 = cA + (size_t)(t + 1) * kstep;
;             const char* a2 = last ? nA : cA + (size_t)(t + 2) * kstep; const char* b2 = last ? nB : cB + (size_t)(t + 2) * kstep;
;             const char* a3 = a2 + kstep; const char* b3 = b2 + kstep;
;             if (last && has_next) S.a_ready(nxt);
;             if constexpr (SP2) {
;             PG8_LDB(B0, 0, 0); PG8_LDB(B1, 0, 1); PG8_SCHED; PG8_LDA(At, 0, 0); PG8_STAGE(PG8_SA(1, 1), a1 + hstep, voffA);
;             PG8_WAIT_V(8); PG8_WAIT_L(0); PG8_BAR; PG8_MMA(0, 0, At, B0); PG8_MMA(0, 1, At, B1); PG8_BAR; PG8_SCHED;
;             PG8_LDA(At, 0, 1); PG8_STAGE(PG8_SB(0, 0), b2, voffB); PG8_STAGE(PG8_SB(0, 1), b2 + hstep, voffB); PG8_STAGE(PG8_SA(0, 0), a2, voffA);
;             PG8_WAIT_V(8); PG8_WAIT_L(0); PG8_BAR; PG8_MMA(1, 0, At, B0); PG8_MMA(1, 1, At, B1); PG8_BAR; PG8_SCHED;
.LBB0_59:
	s_add_u32 s28, s6, 0xfff80080
	s_addc_u32 s29, s7, -1
	s_add_i32 s60, 0, 0x10000
	s_cmp_eq_u32 s59, 28
	s_cselect_b32 s31, s23, s29
	s_cselect_b32 s30, s45, s28
	v_add_u32_e32 v32, s60, v149
	s_cselect_b32 s29, s21, s47
	s_cselect_b32 s28, s57, s58
	s_add_i32 s62, 0, 0x14000
	ds_read_b128 v[142:145], v32
	ds_read_b128 v[152:155], v32 offset:1024
	ds_read_b128 v[156:159], v32 offset:2048
	ds_read_b128 v[160:163], v32 offset:3072
	v_add_u32_e32 v32, s62, v149
	ds_read_b128 v[164:167], v32
	ds_read_b128 v[186:189], v32 offset:1024
	ds_read_b128 v[190:193], v32 offset:2048
	ds_read_b128 v[194:197], v32 offset:3072
	v_lshl_add_u64 v[146:147], s[6:7], 0, v[138:139]
	s_add_i32 m0, s42, 0xc000
	ds_read_b128 v[212:215], v151
	ds_read_b128 v[220:223], v151 offset:1024
	ds_read_b128 v[224:227], v151 offset:2048
	ds_read_b128 v[228:231], v151 offset:3072
	ds_read_b128 v[232:235], v151 offset:4096
	ds_read_b128 v[236:239], v151 offset:5120
	ds_read_b128 v[240:243], v151 offset:6144
	ds_read_b128 v[244:247], v151 offset:7168
	global_load_lds_dwordx4 v[146:147], off
	v_lshl_add_u64 v[146:147], s[6:7], 0, v[140:141]
	s_add_i32 m0, s42, 0xe000
	s_nop 0
	global_load_lds_dwordx4 v[146:147], off
	s_waitcnt vmcnt(8)
	s_waitcnt lgkmcnt(0)
	s_setprio 1
	s_barrier
	v_mfma_f32_16x16x32_bf16 v[126:129], v[142:145], v[212:215], v[126:129]
	v_mfma_f32_16x16x32_bf16 v[122:125], v[156:159], v[212:215], v[122:125]
	v_mfma_f32_16x16x32_bf16 v[110:113], v[142:145], v[224:227], v[110:113]
	v_mfma_f32_16x16x32_bf16 v[106:109], v[156:159], v[224:227], v[106:109]
	v_mfma_f32_16x16x32_bf16 v[94:97], v[142:145], v[232:235], v[94:97]
	v_mfma_f32_16x16x32_bf16 v[90:93], v[156:159], v[232:235], v[90:93]
	v_mfma_f32_16x16x32_bf16 v[78:81], v[142:145], v[240:243], v[78:81]
	v_mfma_f32_16x16x32_bf16 v[74:77], v[156:159], v[240:243], v[74:77]
	v_mfma_f32_16x16x32_bf16 v[126:129], v[152:155], v[220:223], v[126:129]
	v_mfma_f32_16x16x32_bf16 v[122:125], v[160:163], v[220:223], v[122:125]
	v_mfma_f32_16x16x32_bf16 v[110:113], v[152:155], v[228:231], v[110:113]
	v_mfma_f32_16x16x32_bf16 v[106:109], v[160:163], v[228:231], v[106:109]
	v_mfma_f32_16x16x32_bf16 v[94:97], v[152:155], v[236:239], v[94:97]
	v_mfma_f32_16x16x32_bf16 v[90:93], v[160:163], v[236:239], v[90:93]
	v_mfma_f32_16x16x32_bf16 v[78:81], v[152:155], v[244:247], v[78:81]
	v_mfma_f32_16x16x32_bf16 v[74:77], v[160:163], v[244:247], v[74:77]
	v_mfma_f32_16x16x32_bf16 v[118:121], v[164:167], v[212:215], v[118:121]
	v_mfma_f32_16x16x32_bf16 v[114:117], v[190:193], v[212:215], v[114:117]
	v_mfma_f32_16x16x32_bf16 v[102:105], v[164:167], v[224:227], v[102:105]
	v_mfma_f32_16x16x32_bf16 v[98:101], v[190:193], v[224:227], v[98:101]
	v_mfma_f32_16x16x32_bf16 v[86:89], v[164:167], v[232:235], v[86:89]
	v_mfma_f32_16x16x32_bf16 v[82:85], v[190:193], v[232:235], v[82:85]
	v_mfma_f32_16x16x32_bf16 v[70:73], v[164:167], v[240:243], v[70:73]
	v_mfma_f32_16x16x32_bf16 v[66:69], v[190:193], v[240:243], v[66:69]
	v_mfma_f32_16x16x32_bf16 v[118:121], v[186:189], v[220:223], v[118:121]
	v_mfma_f32_16x16x32_bf16 v[114:117], v[194:197], v[220:223], v[114:117]
	v_mfma_f32_16x16x32_bf16 v[102:105], v[186:189], v[228:231], v[102:105]
	v_mfma_f32_16x16x32_bf16 v[98:101], v[194:197], v[228:231], v[98:101]
	v_mfma_f32_16x16x32_bf16 v[86:89], v[186:189], v[236:239], v[86:89]
	v_mfma_f32_16x16x32_bf16 v[82:85], v[194:197], v[236:239], v[82:85]
	v_mfma_f32_16x16x32_bf16 v[70:73], v[186:189], v[244:247], v[70:73]
	v_mfma_f32_16x16x32_bf16 v[66:69], v[194:197], v[244:247], v[66:69]
	s_setprio 0
	s_barrier
	s_add_i32 s60, s60, s39
	v_lshl_add_u64 v[146:147], s[28:29], 0, v[134:135]
	s_mov_b32 m0, s60
	ds_read_b128 v[212:215], v151 offset:16384
	ds_read_b128 v[220:223], v151 offset:17408
	ds_read_b128 v[224:227], v151 offset:18432
	ds_read_b128 v[228:231], v151 offset:19456
	ds_read_b128 v[232:235], v151 offset:20480
	ds_read_b128 v[236:239], v151 offset:21504
	ds_read_b128 v[240:243], v151 offset:22528
	ds_read_b128 v[244:247], v151 offset:23552
	global_load_lds_dwordx4 v[146:147], off
	s_add_i32 m0, s60, 0x2000
	s_add_u32 s60, s28, 0x80000
	v_lshl_add_u64 v[168:169], s[28:29], 0, v[130:131]
	s_addc_u32 s61, s29, 0
	s_add_i32 s62, s62, s39
	global_load_lds_dwordx4 v[168:169], off
	v_lshl_add_u64 v[216:217], s[60:61], 0, v[134:135]
	s_mov_b32 m0, s62
	v_lshl_add_u64 v[248:249], s[30:31], 0, v[132:133]
	global_load_lds_dwordx4 v[216:217], off
	v_lshl_add_u64 v[216:217], s[60:61], 0, v[130:131]
	s_add_i32 m0, s62, 0x2000
	s_nop 0
	global_load_lds_dwordx4 v[216:217], off
	v_lshl_add_u64 v[216:217], s[30:31], 0, v[136:137]
	s_mov_b32 m0, s42
	s_nop 0
	global_load_lds_dwordx4 v[216:217], off
	s_mov_b32 m0, s43
	s_nop 0
	global_load_lds_dwordx4 v[248:249], off
	s_waitcnt vmcnt(8)
	s_waitcnt lgkmcnt(0)
	s_setprio 1
	s_barrier
; #define PG8_STAGE(bufoff, gbase, voff) do { _Pragma("unroll") for (int _i = 0; _i < 2; ++_i) \
;         __builtin_amdgcn_global_load_lds((const unsigned*)((const char*)(gbase) + (voff)[_i]), (PG8_LAS unsigned*)(lds + (bufoff) + ldsw + _i * 8192), 16, 0, 0); } while (0)
; #define PG8_LDA(dst, b, h) do { _Pragma("unroll") for (int m = 0; m < 4; ++m) _Pragma("unroll") for (int k = 0; k < 2; ++k) dst[m][k] = *(const PG8_LAS bf16x8*)(lds + PG8_SA(b, h) + aoff + m * 2048 + k * 1024); } while (0)
; #define PG8_LDB(dst, b, h) do { _Pragma("unroll") for (int n = 0; n < 2; ++n) _Pragma("unroll") for (int k = 0; k < 2; ++k) dst[n][k] = *(const PG8_LAS bf16x8*)(lds + PG8_SB(b, h) + boff + n * 2048 + k * 1024); } while (0)
; #define PG8_MMA(ai, bj, At, Bt) do { __builtin_amdgcn_s_setprio(1); _Pragma("unroll") for (int m = 0; m < 4; ++m) _Pragma("unroll") for (int n = 0; n < 2; ++n) _Pragma("unroll") for (int k = 0; k < 2; ++k) \
;         acc[ai][bj][m][n] = __builtin_amdgcn_mfma_f32_16x16x32_bf16(Bt[n][k], At[m][k], acc[ai][bj][m][n], 0, 0, 0); __builtin_amdgcn_s_setprio(0); } while (0)
; #define PG8_WAIT_V(n) asm volatile("s_waitcnt vmcnt(" #n ")" ::: "memory")
; #define PG8_WAIT_L(n) asm volatile("s_waitcnt lgkmcnt(" #n ")" ::: "memory")
; #define PG8_BAR __builtin_amdgcn_s_barrier()
; #define PG8_SCHED __builtin_amdgcn_sched_barrier(0)
; template <class Epi, class Sched, bool ALIGN_EPI = false, bool SP2 = false>
; __device__ __forceinline__ void gemm_phase(PG8_LAS unsigned char* lds, const Gemm g, const Sched& S, const Epi& E, int tid_in) {
;     ...
;             PG8_WAIT_V(8); PG8_WAIT_L(0); PG8_BAR; PG8_MMA(1, 0, At, B0); PG8_MMA(1, 1, At, B1); PG8_BAR; PG8_SCHED;
;             PG8_LDB(B0, 1, 0); PG8_LDB(B1, 1, 1); PG8_SCHED; PG8_LDA(At, 1, 0); PG8_STAGE(PG8_SA(0, 1), a2 + hstep, voffA);
;             PG8_WAIT_V(8); PG8_WAIT_L(0); PG8_BAR; PG8_MMA(0, 0, At, B0); PG8_MMA(0, 1, At, B1); PG8_BAR; PG8_SCHED;
	v_mfma_f32_16x16x32_bf16 v[62:65], v[142:145], v[212:215], v[62:65]
	v_mfma_f32_16x16x32_bf16 v[58:61], v[156:159], v[212:215], v[58:61]
	v_mfma_f32_16x16x32_bf16 v[46:49], v[142:145], v[224:227], v[46:49]
	v_mfma_f32_16x16x32_bf16 v[42:45], v[156:159], v[224:227], v[42:45]
	v_mfma_f32_16x16x32_bf16 v[28:31], v[142:145], v[232:235], v[28:31]
	v_mfma_f32_16x16x32_bf16 v[24:27], v[156:159], v[232:235], v[24:27]
	v_mfma_f32_16x16x32_bf16 v[12:15], v[142:145], v[240:243], v[12:15]
	v_mfma_f32_16x16x32_bf16 v[8:11], v[156:159], v[240:243], v[8:11]
	v_mfma_f32_16x16x32_bf16 v[62:65], v[152:155], v[220:223], v[62:65]
	v_mfma_f32_16x16x32_bf16 v[58:61], v[160:163], v[220:223], v[58:61]
	v_mfma_f32_16x16x32_bf16 v[46:49], v[152:155], v[228:231], v[46:49]
	v_mfma_f32_16x16x32_bf16 v[42:45], v[160:163], v[228:231], v[42:45]
	v_mfma_f32_16x16x32_bf16 v[28:31], v[152:155], v[236:239], v[28:31]
	v_mfma_f32_16x16x32_bf16 v[24:27], v[160:163], v[236:239], v[24:27]
	v_mfma_f32_16x16x32_bf16 v[12:15], v[152:155], v[244:247], v[12:15]
	v_mfma_f32_16x16x32_bf16 v[8:11], v[160:163], v[244:247], v[8:11]
	v_mfma_f32_16x16x32_bf16 v[54:57], v[164:167], v[212:215], v[54:57]
	v_mfma_f32_16x16x32_bf16 v[50:53], v[190:193], v[212:215], v[50:53]
	v_mfma_f32_16x16x32_bf16 v[38:41], v[164:167], v[224:227], v[38:41]
	v_mfma_f32_16x16x32_bf16 v[34:37], v[190:193], v[224:227], v[34:37]
	v_mfma_f32_16x16x32_bf16 v[20:23], v[164:167], v[232:235], v[20:23]
	v_mfma_f32_16x16x32_bf16 v[16:19], v[190:193], v[232:235], v[16:19]
	v_mfma_f32_16x16x32_bf16 v[4:7], v[164:167], v[240:243], v[4:7]
	v_mfma_f32_16x16x32_bf16 v[0:3], v[190:193], v[240:243], v[0:3]
	v_mfma_f32_16x16x32_bf16 v[54:57], v[186:189], v[220:223], v[54:57]
	v_mfma_f32_16x16x32_bf16 v[50:53], v[194:197], v[220:223], v[50:53]
	v_mfma_f32_16x16x32_bf16 v[38:41], v[186:189], v[228:231], v[38:41]
	v_mfma_f32_16x16x32_bf16 v[34:37], v[194:197], v[228:231], v[34:37]
	v_mfma_f32_16x16x32_bf16 v[20:23], v[186:189], v[236:239], v[20:23]
	v_mfma_f32_16x16x32_bf16 v[16:19], v[194:197], v[236:239], v[16:19]
	v_mfma_f32_16x16x32_bf16 v[4:7], v[186:189], v[244:247], v[4:7]
	v_mfma_f32_16x16x32_bf16 v[0:3], v[194:197], v[244:247], v[0:3]
	s_setprio 0
	s_barrier
	s_add_i32 s60, 0, 0x18000
	v_add_u32_e32 v32, s60, v149
	s_add_i32 s61, 0, 0x1c000
	ds_read_b128 v[142:145], v32
	ds_read_b128 v[152:155], v32 offset:1024
	ds_read_b128 v[156:159], v32 offset:2048
	ds_read_b128 v[160:163], v32 offset:3072
	v_add_u32_e32 v32, s61, v149
	ds_read_b128 v[164:167], v32
	ds_read_b128 v[186:189], v32 offset:1024
	ds_read_b128 v[190:193], v32 offset:2048
	ds_read_b128 v[194:197], v32 offset:3072
	s_add_u32 s30, s30, 0x80000
	s_addc_u32 s31, s31, 0
	s_mov_b32 m0, s48
	v_lshl_add_u64 v[250:251], s[30:31], 0, v[136:137]
	ds_read_b128 v[212:215], v151 offset:32768
	ds_read_b128 v[220:223], v151 offset:33792
	ds_read_b128 v[224:227], v151 offset:34816
	ds_read_b128 v[228:231], v151 offset:35840
	ds_read_b128 v[232:235], v151 offset:36864
	ds_read_b128 v[236:239], v151 offset:37888
	ds_read_b128 v[240:243], v151 offset:38912
	ds_read_b128 v[244:247], v151 offset:39936
	global_load_lds_dwordx4 v[250:251], off
	v_lshl_add_u64 v[250:251], s[30:31], 0, v[132:133]
	s_mov_b32 m0, s49
	s_nop 0
	global_load_lds_dwordx4 v[250:251], off
	s_waitcnt vmcnt(8)
	s_waitcnt lgkmcnt(0)
	s_setprio 1
	s_barrier
	v_mfma_f32_16x16x32_bf16 v[126:129], v[142:145], v[212:215], v[126:129]
	v_mfma_f32_16x16x32_bf16 v[122:125], v[156:159], v[212:215], v[122:125]
	v_mfma_f32_16x16x32_bf16 v[110:113], v[142:145], v[224:227], v[110:113]
	v_mfma_f32_16x16x32_bf16 v[106:109], v[156:159], v[224:227], v[106:109]
	v_mfma_f32_16x16x32_bf16 v[94:97], v[142:145], v[232:235], v[94:97]
	v_mfma_f32_16x16x32_bf16 v[90:93], v[156:159], v[232:235], v[90:93]
	v_mfma_f32_16x16x32_bf16 v[78:81], v[142:145], v[240:243], v[78:81]
	v_mfma_f32_16x16x32_bf16 v[74:77], v[156:159], v[240:243], v[74:77]
	v_mfma_f32_16x16x32_bf16 v[126:129], v[152:155], v[220:223], v[126:129]
	v_mfma_f32_16x16x32_bf16 v[122:125], v[160:163], v[220:223], v[122:125]
	v_mfma_f32_16x16x32_bf16 v[110:113], v[152:155], v[228:231], v[110:113]
	v_mfma_f32_16x16x32_bf16 v[106:109], v[160:163], v[228:231], v[106:109]
	v_mfma_f32_16x16x32_bf16 v[94:97], v[152:155], v[236:239], v[94:97]
	v_mfma_f32_16x16x32_bf16 v[90:93], v[160:163], v[236:239], v[90:93]
	v_mfma_f32_16x16x32_bf16 v[78:81], v[152:155], v[244:247], v[78:81]
	v_mfma_f32_16x16x32_bf16 v[74:77], v[160:163], v[244:247], v[74:77]
	v_mfma_f32_16x16x32_bf16 v[118:121], v[164:167], v[212:215], v[118:121]
	v_mfma_f32_16x16x32_bf16 v[114:117], v[190:193], v[212:215], v[114:117]
	v_mfma_f32_16x16x32_bf16 v[102:105], v[164:167], v[224:227], v[102:105]
	v_mfma_f32_16x16x32_bf16 v[98:101], v[190:193], v[224:227], v[98:101]
	v_mfma_f32_16x16x32_bf16 v[86:89], v[164:167], v[232:235], v[86:89]
	v_mfma_f32_16x16x32_bf16 v[82:85], v[190:193], v[232:235], v[82:85]
	v_mfma_f32_16x16x32_bf16 v[70:73], v[164:167], v[240:243], v[70:73]
	v_mfma_f32_16x16x32_bf16 v[66:69], v[190:193], v[240:243], v[66:69]
	v_mfma_f32_16x16x32_bf16 v[118:121], v[186:189], v[220:223], v[118:121]
	v_mfma_f32_16x16x32_bf16 v[114:117], v[194:197], v[220:223], v[114:117]
	v_mfma_f32_16x16x32_bf16 v[102:105], v[186:189], v[228:231], v[102:105]
	v_mfma_f32_16x16x32_bf16 v[98:101], v[194:197], v[228:231], v[98:101]
	v_mfma_f32_16x16x32_bf16 v[86:89], v[186:189], v[236:239], v[86:89]
	v_mfma_f32_16x16x32_bf16 v[82:85], v[194:197], v[236:239], v[82:85]
	v_mfma_f32_16x16x32_bf16 v[70:73], v[186:189], v[244:247], v[70:73]
	v_mfma_f32_16x16x32_bf16 v[66:69], v[194:197], v[244:247], v[66:69]
	s_setprio 0
	s_barrier
; #define PG8_STAGE(bufoff, gbase, voff) do { _Pragma("unroll") for (int _i = 0; _i < 2; ++_i) \
;         __builtin_amdgcn_global_load_lds((const unsigned*)((const char*)(gbase) + (voff)[_i]), (PG8_LAS unsigned*)(lds + (bufoff) + ldsw + _i * 8192), 16, 0, 0); } while (0)
; #define PG8_LDA(dst, b, h) do { _Pragma("unroll") for (int m = 0; m < 4; ++m) _Pragma("unroll") for (int k = 0; k < 2; ++k) dst[m][k] = *(const PG8_LAS bf16x8*)(lds + PG8_SA(b, h) + aoff + m * 2048 + k * 1024); } while (0)
; #define PG8_MMA(ai, bj, At, Bt) do { __builtin_amdgcn_s_setprio(1); _Pragma("unroll") for (int m = 0; m < 4; ++m) _Pragma("unroll") for (int n = 0; n < 2; ++n) _Pragma("unroll") for (int k = 0; k < 2; ++k) \
;         acc[ai][bj][m][n] = __builtin_amdgcn_mfma_f32_16x16x32_bf16(Bt[n][k], At[m][k], acc[ai][bj][m][n], 0, 0, 0); __builtin_amdgcn_s_setprio(0); } while (0)
; #define PG8_WAIT_V(n) asm volatile("s_waitcnt vmcnt(" #n ")" ::: "memory")
; #define PG8_WAIT_L(n) asm volatile("s_waitcnt lgkmcnt(" #n ")" ::: "memory")
; #define PG8_BAR __builtin_amdgcn_s_barrier()
; #define PG8_SCHED __builtin_amdgcn_sched_barrier(0)
; template <class Epi, class Sched, bool ALIGN_EPI = false, bool SP2 = false>
; __device__ __forceinline__ void gemm_phase(PG8_LAS unsigned char* lds, const Gemm g, const Sched& S, const Epi& E, int tid_in) {
;     ...
;         for (int t = 0; t < nt; t += 2) {
;     ...
;             PG8_LDA(At, 1, 1); PG8_STAGE(PG8_SB(1, 0), b3, voffB); PG8_STAGE(PG8_SB(1, 1), b3 + hstep, voffB); PG8_STAGE(PG8_SA(1, 0), a3, voffA);
;             PG8_WAIT_V(8); PG8_WAIT_L(0); PG8_BAR; PG8_MMA(1, 0, At, B0); PG8_MMA(1, 1, At, B1); PG8_BAR; PG8_SCHED;
	s_add_i32 s30, s60, s39
	v_lshl_add_u64 v[146:147], v[146:147], 0, s[74:75]
	s_mov_b32 m0, s30
	ds_read_b128 v[212:215], v151 offset:49152
	ds_read_b128 v[220:223], v151 offset:50176
	ds_read_b128 v[224:227], v151 offset:51200
	ds_read_b128 v[228:231], v151 offset:52224
	ds_read_b128 v[232:235], v151 offset:53248
	ds_read_b128 v[236:239], v151 offset:54272
	ds_read_b128 v[240:243], v151 offset:55296
	ds_read_b128 v[244:247], v151 offset:56320
	global_load_lds_dwordx4 v[146:147], off
	s_add_i32 m0, s30, 0x2000
	s_add_u32 s28, s28, 0x80080
	v_lshl_add_u64 v[146:147], v[168:169], 0, s[74:75]
	s_addc_u32 s29, s29, 0
	s_add_i32 s30, s61, s39
	global_load_lds_dwordx4 v[146:147], off
	v_lshl_add_u64 v[146:147], s[28:29], 0, v[134:135]
	s_mov_b32 m0, s30
	s_nop 0
	global_load_lds_dwordx4 v[146:147], off
	v_lshl_add_u64 v[146:147], s[28:29], 0, v[130:131]
	s_add_i32 m0, s30, 0x2000
	s_nop 0
	global_load_lds_dwordx4 v[146:147], off
	v_lshl_add_u64 v[146:147], v[216:217], 0, s[74:75]
	s_mov_b32 m0, s50
	s_nop 0
	global_load_lds_dwordx4 v[146:147], off
	v_lshl_add_u64 v[146:147], v[248:249], 0, s[74:75]
	s_mov_b32 m0, s51
	s_nop 0
	global_load_lds_dwordx4 v[146:147], off
	s_waitcnt vmcnt(8)
	s_waitcnt lgkmcnt(0)
	s_setprio 1
	s_barrier
	v_mfma_f32_16x16x32_bf16 v[62:65], v[142:145], v[212:215], v[62:65]
	v_mfma_f32_16x16x32_bf16 v[58:61], v[156:159], v[212:215], v[58:61]
	v_mfma_f32_16x16x32_bf16 v[46:49], v[142:145], v[224:227], v[46:49]
	v_mfma_f32_16x16x32_bf16 v[42:45], v[156:159], v[224:227], v[42:45]
	v_mfma_f32_16x16x32_bf16 v[28:31], v[142:145], v[232:235], v[28:31]
	v_mfma_f32_16x16x32_bf16 v[24:27], v[156:159], v[232:235], v[24:27]
	v_mfma_f32_16x16x32_bf16 v[12:15], v[142:145], v[240:243], v[12:15]
	v_mfma_f32_16x16x32_bf16 v[8:11], v[156:159], v[240:243], v[8:11]
	v_mfma_f32_16x16x32_bf16 v[62:65], v[152:155], v[220:223], v[62:65]
	v_mfma_f32_16x16x32_bf16 v[58:61], v[160:163], v[220:223], v[58:61]
	v_mfma_f32_16x16x32_bf16 v[46:49], v[152:155], v[228:231], v[46:49]
	v_mfma_f32_16x16x32_bf16 v[42:45], v[160:163], v[228:231], v[42:45]
	v_mfma_f32_16x16x32_bf16 v[28:31], v[152:155], v[236:239], v[28:31]
	v_mfma_f32_16x16x32_bf16 v[24:27], v[160:163], v[236:239], v[24:27]
	v_mfma_f32_16x16x32_bf16 v[12:15], v[152:155], v[244:247], v[12:15]
	v_mfma_f32_16x16x32_bf16 v[8:11], v[160:163], v[244:247], v[8:11]
	v_mfma_f32_16x16x32_bf16 v[54:57], v[164:167], v[212:215], v[54:57]
	v_mfma_f32_16x16x32_bf16 v[50:53], v[190:193], v[212:215], v[50:53]
	v_mfma_f32_16x16x32_bf16 v[38:41], v[164:167], v[224:227], v[38:41]
	v_mfma_f32_16x16x32_bf16 v[34:37], v[190:193], v[224:227], v[34:37]
	v_mfma_f32_16x16x32_bf16 v[20:23], v[164:167], v[232:235], v[20:23]
	v_mfma_f32_16x16x32_bf16 v[16:19], v[190:193], v[232:235], v[16:19]
	v_mfma_f32_16x16x32_bf16 v[4:7], v[164:167], v[240:243], v[4:7]
	v_mfma_f32_16x16x32_bf16 v[0:3], v[190:193], v[240:243], v[0:3]
	v_mfma_f32_16x16x32_bf16 v[54:57], v[186:189], v[220:223], v[54:57]
	v_mfma_f32_16x16x32_bf16 v[50:53], v[194:197], v[220:223], v[50:53]
	v_mfma_f32_16x16x32_bf16 v[38:41], v[186:189], v[228:231], v[38:41]
	v_mfma_f32_16x16x32_bf16 v[34:37], v[194:197], v[228:231], v[34:37]
	v_mfma_f32_16x16x32_bf16 v[20:23], v[186:189], v[236:239], v[20:23]
	v_mfma_f32_16x16x32_bf16 v[16:19], v[194:197], v[236:239], v[16:19]
	v_mfma_f32_16x16x32_bf16 v[4:7], v[186:189], v[244:247], v[4:7]
	v_mfma_f32_16x16x32_bf16 v[0:3], v[194:197], v[244:247], v[0:3]
	s_setprio 0
	s_barrier
	s_add_i32 s59, s59, 2
	s_add_u32 s6, s6, 0x100
	s_addc_u32 s7, s7, 0
	s_add_u32 s58, s58, 0x100
	s_addc_u32 s47, s47, 0
	s_cmp_gt_u32 s59, 29
	s_cbranch_scc0 .LBB0_59
	s_and_b64 vcc, exec, s[16:17]
	s_cbranch_vccz .LBB0_62
	s_barrier

; #define PG8_STAGE(bufoff, gbase, voff) do { _Pragma("unroll") for (int _i = 0; _i < 2; ++_i) \
;         __builtin_amdgcn_global_load_lds((const unsigned*)((const char*)(gbase) + (voff)[_i]), (PG8_LAS unsigned*)(lds + (bufoff) + ldsw + _i * 8192), 16, 0, 0); } while (0)
; #define PG8_LDA(dst, b, h) do { _Pragma("unroll") for (int m = 0; m < 4; ++m) _Pragma("unroll") for (int k = 0; k < 2; ++k) dst[m][k] = *(const PG8_LAS bf16x8*)(lds + PG8_SA(b, h) + aoff + m * 2048 + k * 1024); } while (0)
; #define PG8_LDB(dst, b, h) do { _Pragma("unroll") for (int n = 0; n < 2; ++n) _Pragma("unroll") for (int k = 0; k < 2; ++k) dst[n][k] = *(const PG8_LAS bf16x8*)(lds + PG8_SB(b, h) + boff + n * 2048 + k * 1024); } while (0)
; #define PG8_MMA(ai, bj, At, Bt) do { __builtin_amdgcn_s_setprio(1); _Pragma("unroll") for (int m = 0; m < 4; ++m) _Pragma("unroll") for (int n = 0; n < 2; ++n) _Pragma("unroll") for (int k = 0; k < 2; ++k) \
;         acc[ai][bj][m][n] = __builtin_amdgcn_mfma_f32_16x16x32_bf16(Bt[n][k], At[m][k], acc[ai][bj][m][n], 0, 0, 0); __builtin_amdgcn_s_setprio(0); } while (0)
; #define PG8_WAIT_V(n) asm volatile("s_waitcnt vmcnt(" #n ")" ::: "memory")
; #define PG8_WAIT_L(n) asm volatile("s_waitcnt lgkmcnt(" #n ")" ::: "memory")
; template <class Epi, class Sched, bool ALIGN_EPI = false, bool SP2 = false>
; __device__ __forceinline__ void gemm_phase(PG8_LAS unsigned char* lds, const Gemm g, const Sched& S, const Epi& E, int tid_in) {
;     ...
;             const bool last = (t == nt - 2);
;             const char* a1 = cA + (size_t)(t + 1) * kstep;
;             const char* a2 = last ? nA : cA + (size_t)(t + 2) * kstep; const char* b2 = last ? nB : cB + (size_t)(t + 2) * kstep;
;             const char* a3 = a2 + kstep; const char* b3 = b2 + kstep;
;             if (last && has_next) S.a_ready(nxt);
;             if constexpr (SP2) {
;             PG8_LDB(B0, 0, 0); PG8_LDB(B1, 0, 1); PG8_SCHED; PG8_LDA(At, 0, 0); PG8_STAGE(PG8_SA(1, 1), a1 + hstep, voffA);
;             PG8_WAIT_V(8); PG8_WAIT_L(0); PG8_BAR; PG8_MMA(0, 0, At, B0); PG8_MMA(0, 1, At, B1); PG8_BAR; PG8_SCHED;
;             PG8_LDA(At, 0, 1); PG8_STAGE(PG8_SB(0, 0), b2, voffB); PG8_STAGE(PG8_SB(0, 1), b2 + hstep, voffB); PG8_STAGE(PG8_SA(0, 0), a2, voffA);
;             PG8_WAIT_V(8); PG8_WAIT_L(0); PG8_BAR; PG8_MMA(1, 0, At, B0); PG8_MMA(1, 1, At, B1); PG8_BAR; PG8_SCHED;
.LBB0_349:
	s_add_u32 s26, s24, 0x100
	s_addc_u32 s27, s25, 0
	s_add_i32 s60, 0, 0x10000
	s_cmp_eq_u32 s59, 28
	s_cselect_b32 s31, s19, s27
	s_cselect_b32 s30, s45, s26
	s_cselect_b32 s29, s17, s58
	s_cselect_b32 s28, s57, s47
	s_add_i32 s61, 0, 0x14000
	v_add_u32_e32 v152, s60, v141
	v_add_u32_e32 v168, s61, v141
	ds_read_b128 v[136:139], v152
	ds_read_b128 v[144:147], v152 offset:1024
	ds_read_b128 v[148:151], v152 offset:2048
	ds_read_b128 v[152:155], v152 offset:3072
	ds_read_b128 v[156:159], v168
	ds_read_b128 v[160:163], v168 offset:1024
	ds_read_b128 v[164:167], v168 offset:2048
	ds_read_b128 v[186:189], v168 offset:3072
	v_lshl_add_u64 v[168:169], s[24:25], 0, v[132:133]
	s_add_i32 m0, s39, 0xc000
	ds_read_b128 v[190:193], v143
	ds_read_b128 v[194:197], v143 offset:1024
	ds_read_b128 v[212:215], v143 offset:2048
	ds_read_b128 v[220:223], v143 offset:3072
	ds_read_b128 v[224:227], v143 offset:4096
	ds_read_b128 v[228:231], v143 offset:5120
	ds_read_b128 v[232:235], v143 offset:6144
	ds_read_b128 v[236:239], v143 offset:7168
	global_load_lds_dwordx4 v[168:169], off
	v_lshl_add_u64 v[168:169], s[24:25], 0, v[134:135]
	s_add_i32 m0, s39, 0xe000
	s_nop 0
	global_load_lds_dwordx4 v[168:169], off
	s_waitcnt vmcnt(8)
	s_waitcnt lgkmcnt(0)
	s_setprio 1
	s_barrier
	v_mfma_f32_16x16x32_bf16 v[126:129], v[136:139], v[190:193], v[126:129]
	v_mfma_f32_16x16x32_bf16 v[122:125], v[148:151], v[190:193], v[122:125]
	v_mfma_f32_16x16x32_bf16 v[114:117], v[136:139], v[212:215], v[114:117]
	v_mfma_f32_16x16x32_bf16 v[110:113], v[148:151], v[212:215], v[110:113]
	v_mfma_f32_16x16x32_bf16 v[98:101], v[136:139], v[224:227], v[98:101]
	v_mfma_f32_16x16x32_bf16 v[94:97], v[148:151], v[224:227], v[94:97]
	v_mfma_f32_16x16x32_bf16 v[82:85], v[136:139], v[232:235], v[82:85]
	v_mfma_f32_16x16x32_bf16 v[78:81], v[148:151], v[232:235], v[78:81]
	v_mfma_f32_16x16x32_bf16 v[126:129], v[144:147], v[194:197], v[126:129]
	v_mfma_f32_16x16x32_bf16 v[122:125], v[152:155], v[194:197], v[122:125]
	v_mfma_f32_16x16x32_bf16 v[114:117], v[144:147], v[220:223], v[114:117]
	v_mfma_f32_16x16x32_bf16 v[110:113], v[152:155], v[220:223], v[110:113]
	v_mfma_f32_16x16x32_bf16 v[98:101], v[144:147], v[228:231], v[98:101]
	v_mfma_f32_16x16x32_bf16 v[94:97], v[152:155], v[228:231], v[94:97]
	v_mfma_f32_16x16x32_bf16 v[82:85], v[144:147], v[236:239], v[82:85]
	v_mfma_f32_16x16x32_bf16 v[78:81], v[152:155], v[236:239], v[78:81]
	v_mfma_f32_16x16x32_bf16 v[118:121], v[156:159], v[190:193], v[118:121]
	v_mfma_f32_16x16x32_bf16 v[106:109], v[164:167], v[190:193], v[106:109]
	v_mfma_f32_16x16x32_bf16 v[102:105], v[156:159], v[212:215], v[102:105]
	v_mfma_f32_16x16x32_bf16 v[90:93], v[164:167], v[212:215], v[90:93]
	v_mfma_f32_16x16x32_bf16 v[86:89], v[156:159], v[224:227], v[86:89]
	v_mfma_f32_16x16x32_bf16 v[74:77], v[164:167], v[224:227], v[74:77]
	v_mfma_f32_16x16x32_bf16 v[70:73], v[156:159], v[232:235], v[70:73]
	v_mfma_f32_16x16x32_bf16 v[66:69], v[164:167], v[232:235], v[66:69]
	v_mfma_f32_16x16x32_bf16 v[118:121], v[160:163], v[194:197], v[118:121]
	v_mfma_f32_16x16x32_bf16 v[106:109], v[186:189], v[194:197], v[106:109]
	v_mfma_f32_16x16x32_bf16 v[102:105], v[160:163], v[220:223], v[102:105]
	v_mfma_f32_16x16x32_bf16 v[90:93], v[186:189], v[220:223], v[90:93]
	v_mfma_f32_16x16x32_bf16 v[86:89], v[160:163], v[228:231], v[86:89]
	v_mfma_f32_16x16x32_bf16 v[74:77], v[186:189], v[228:231], v[74:77]
	v_mfma_f32_16x16x32_bf16 v[70:73], v[160:163], v[236:239], v[70:73]
	v_mfma_f32_16x16x32_bf16 v[66:69], v[186:189], v[236:239], v[66:69]
	s_setprio 0
	s_barrier
	s_add_i32 s24, s60, s4
	v_lshl_add_u64 v[168:169], s[28:29], 0, v[32:33]
	s_mov_b32 m0, s24
	ds_read_b128 v[190:193], v143 offset:16384
	ds_read_b128 v[194:197], v143 offset:17408
	ds_read_b128 v[212:215], v143 offset:18432
	ds_read_b128 v[220:223], v143 offset:19456
	ds_read_b128 v[224:227], v143 offset:20480
	ds_read_b128 v[228:231], v143 offset:21504
	ds_read_b128 v[232:235], v143 offset:22528
	ds_read_b128 v[236:239], v143 offset:23552
	global_load_lds_dwordx4 v[168:169], off
	s_add_i32 m0, s24, 0x2000
	s_add_u32 s24, s28, 0x80000
	v_lshl_add_u64 v[216:217], s[28:29], 0, v[130:131]
	s_addc_u32 s25, s29, 0
	s_add_i32 s60, s61, s4
	global_load_lds_dwordx4 v[216:217], off
	v_lshl_add_u64 v[240:241], s[24:25], 0, v[32:33]
	s_mov_b32 m0, s60
	v_lshl_add_u64 v[242:243], s[30:31], 0, v[130:131]
	global_load_lds_dwordx4 v[240:241], off
	v_lshl_add_u64 v[240:241], s[24:25], 0, v[130:131]
	s_add_i32 m0, s60, 0x2000
	s_nop 0
	global_load_lds_dwordx4 v[240:241], off
	v_lshl_add_u64 v[240:241], s[30:31], 0, v[32:33]
	s_mov_b32 m0, s39
	s_nop 0
	global_load_lds_dwordx4 v[240:241], off
	s_mov_b32 m0, s42
	s_nop 0
	global_load_lds_dwordx4 v[242:243], off
	s_waitcnt vmcnt(8)
	s_waitcnt lgkmcnt(0)
	s_setprio 1
	s_barrier
; #define PG8_STAGE(bufoff, gbase, voff) do { _Pragma("unroll") for (int _i = 0; _i < 2; ++_i) \
;         __builtin_amdgcn_global_load_lds((const unsigned*)((const char*)(gbase) + (voff)[_i]), (PG8_LAS unsigned*)(lds + (bufoff) + ldsw + _i * 8192), 16, 0, 0); } while (0)
; #define PG8_LDA(dst, b, h) do { _Pragma("unroll") for (int m = 0; m < 4; ++m) _Pragma("unroll") for (int k = 0; k < 2; ++k) dst[m][k] = *(const PG8_LAS bf16x8*)(lds + PG8_SA(b, h) + aoff + m * 2048 + k * 1024); } while (0)
; #define PG8_LDB(dst, b, h) do { _Pragma("unroll") for (int n = 0; n < 2; ++n) _Pragma("unroll") for (int k = 0; k < 2; ++k) dst[n][k] = *(const PG8_LAS bf16x8*)(lds + PG8_SB(b, h) + boff + n * 2048 + k * 1024); } while (0)
; #define PG8_MMA(ai, bj, At, Bt) do { __builtin_amdgcn_s_setprio(1); _Pragma("unroll") for (int m = 0; m < 4; ++m) _Pragma("unroll") for (int n = 0; n < 2; ++n) _Pragma("unroll") for (int k = 0; k < 2; ++k) \
;         acc[ai][bj][m][n] = __builtin_amdgcn_mfma_f32_16x16x32_bf16(Bt[n][k], At[m][k], acc[ai][bj][m][n], 0, 0, 0); __builtin_amdgcn_s_setprio(0); } while (0)
; #define PG8_WAIT_V(n) asm volatile("s_waitcnt vmcnt(" #n ")" ::: "memory")
; #define PG8_WAIT_L(n) asm volatile("s_waitcnt lgkmcnt(" #n ")" ::: "memory")
; #define PG8_BAR __builtin_amdgcn_s_barrier()
; #define PG8_SCHED __builtin_amdgcn_sched_barrier(0)
; template <class Epi, class Sched, bool ALIGN_EPI = false, bool SP2 = false>
; __device__ __forceinline__ void gemm_phase(PG8_LAS unsigned char* lds, const Gemm g, const Sched& S, const Epi& E, int tid_in) {
;     ...
;             PG8_WAIT_V(8); PG8_WAIT_L(0); PG8_BAR; PG8_MMA(1, 0, At, B0); PG8_MMA(1, 1, At, B1); PG8_BAR; PG8_SCHED;
;             PG8_LDB(B0, 1, 0); PG8_LDB(B1, 1, 1); PG8_SCHED; PG8_LDA(At, 1, 0); PG8_STAGE(PG8_SA(0, 1), a2 + hstep, voffA);
;             PG8_WAIT_V(8); PG8_WAIT_L(0); PG8_BAR; PG8_MMA(0, 0, At, B0); PG8_MMA(0, 1, At, B1); PG8_BAR; PG8_SCHED;
	v_mfma_f32_16x16x32_bf16 v[62:65], v[136:139], v[190:193], v[62:65]
	v_mfma_f32_16x16x32_bf16 v[58:61], v[148:151], v[190:193], v[58:61]
	v_mfma_f32_16x16x32_bf16 v[50:53], v[136:139], v[212:215], v[50:53]
	v_mfma_f32_16x16x32_bf16 v[46:49], v[148:151], v[212:215], v[46:49]
	v_mfma_f32_16x16x32_bf16 v[34:37], v[136:139], v[224:227], v[34:37]
	v_mfma_f32_16x16x32_bf16 v[28:31], v[148:151], v[224:227], v[28:31]
	v_mfma_f32_16x16x32_bf16 v[16:19], v[136:139], v[232:235], v[16:19]
	v_mfma_f32_16x16x32_bf16 v[12:15], v[148:151], v[232:235], v[12:15]
	v_mfma_f32_16x16x32_bf16 v[62:65], v[144:147], v[194:197], v[62:65]
	v_mfma_f32_16x16x32_bf16 v[58:61], v[152:155], v[194:197], v[58:61]
	v_mfma_f32_16x16x32_bf16 v[50:53], v[144:147], v[220:223], v[50:53]
	v_mfma_f32_16x16x32_bf16 v[46:49], v[152:155], v[220:223], v[46:49]
	v_mfma_f32_16x16x32_bf16 v[34:37], v[144:147], v[228:231], v[34:37]
	v_mfma_f32_16x16x32_bf16 v[28:31], v[152:155], v[228:231], v[28:31]
	v_mfma_f32_16x16x32_bf16 v[16:19], v[144:147], v[236:239], v[16:19]
	v_mfma_f32_16x16x32_bf16 v[12:15], v[152:155], v[236:239], v[12:15]
	v_mfma_f32_16x16x32_bf16 v[54:57], v[156:159], v[190:193], v[54:57]
	v_mfma_f32_16x16x32_bf16 v[42:45], v[164:167], v[190:193], v[42:45]
	v_mfma_f32_16x16x32_bf16 v[38:41], v[156:159], v[212:215], v[38:41]
	v_mfma_f32_16x16x32_bf16 v[24:27], v[164:167], v[212:215], v[24:27]
	v_mfma_f32_16x16x32_bf16 v[20:23], v[156:159], v[224:227], v[20:23]
	v_mfma_f32_16x16x32_bf16 v[8:11], v[164:167], v[224:227], v[8:11]
	v_mfma_f32_16x16x32_bf16 v[4:7], v[156:159], v[232:235], v[4:7]
	v_mfma_f32_16x16x32_bf16 v[0:3], v[164:167], v[232:235], v[0:3]
	v_mfma_f32_16x16x32_bf16 v[54:57], v[160:163], v[194:197], v[54:57]
	v_mfma_f32_16x16x32_bf16 v[42:45], v[186:189], v[194:197], v[42:45]
	v_mfma_f32_16x16x32_bf16 v[38:41], v[160:163], v[220:223], v[38:41]
	v_mfma_f32_16x16x32_bf16 v[24:27], v[186:189], v[220:223], v[24:27]
	v_mfma_f32_16x16x32_bf16 v[20:23], v[160:163], v[228:231], v[20:23]
	v_mfma_f32_16x16x32_bf16 v[8:11], v[186:189], v[228:231], v[8:11]
	v_mfma_f32_16x16x32_bf16 v[4:7], v[160:163], v[236:239], v[4:7]
	v_mfma_f32_16x16x32_bf16 v[0:3], v[186:189], v[236:239], v[0:3]
	s_setprio 0
	s_barrier
	s_add_i32 s60, 0, 0x18000
	s_add_i32 s61, 0, 0x1c000
	v_add_u32_e32 v152, s60, v141
	v_add_u32_e32 v170, s61, v141
	ds_read_b128 v[136:139], v152
	ds_read_b128 v[144:147], v152 offset:1024
	ds_read_b128 v[148:151], v152 offset:2048
	ds_read_b128 v[152:155], v152 offset:3072
	ds_read_b128 v[156:159], v170
	ds_read_b128 v[160:163], v170 offset:1024
	ds_read_b128 v[164:167], v170 offset:2048
	ds_read_b128 v[186:189], v170 offset:3072
	s_add_u32 s24, s30, 0x80000
	s_addc_u32 s25, s31, 0
	s_mov_b32 m0, s43
	v_lshl_add_u64 v[244:245], s[24:25], 0, v[32:33]
	ds_read_b128 v[190:193], v143 offset:32768
	ds_read_b128 v[194:197], v143 offset:33792
	ds_read_b128 v[212:215], v143 offset:34816
	ds_read_b128 v[220:223], v143 offset:35840
	ds_read_b128 v[224:227], v143 offset:36864
	ds_read_b128 v[228:231], v143 offset:37888
	ds_read_b128 v[232:235], v143 offset:38912
	ds_read_b128 v[236:239], v143 offset:39936
	global_load_lds_dwordx4 v[244:245], off
	v_lshl_add_u64 v[244:245], s[24:25], 0, v[130:131]
	s_mov_b32 m0, s48
	s_nop 0
	global_load_lds_dwordx4 v[244:245], off
	s_waitcnt vmcnt(8)
	s_waitcnt lgkmcnt(0)
	s_setprio 1
	s_barrier
	v_mfma_f32_16x16x32_bf16 v[126:129], v[136:139], v[190:193], v[126:129]
	v_mfma_f32_16x16x32_bf16 v[122:125], v[148:151], v[190:193], v[122:125]
	v_mfma_f32_16x16x32_bf16 v[114:117], v[136:139], v[212:215], v[114:117]
	v_mfma_f32_16x16x32_bf16 v[110:113], v[148:151], v[212:215], v[110:113]
	v_mfma_f32_16x16x32_bf16 v[98:101], v[136:139], v[224:227], v[98:101]
	v_mfma_f32_16x16x32_bf16 v[94:97], v[148:151], v[224:227], v[94:97]
	v_mfma_f32_16x16x32_bf16 v[82:85], v[136:139], v[232:235], v[82:85]
	v_mfma_f32_16x16x32_bf16 v[78:81], v[148:151], v[232:235], v[78:81]
	v_mfma_f32_16x16x32_bf16 v[126:129], v[144:147], v[194:197], v[126:129]
	v_mfma_f32_16x16x32_bf16 v[122:125], v[152:155], v[194:197], v[122:125]
	v_mfma_f32_16x16x32_bf16 v[114:117], v[144:147], v[220:223], v[114:117]
	v_mfma_f32_16x16x32_bf16 v[110:113], v[152:155], v[220:223], v[110:113]
	v_mfma_f32_16x16x32_bf16 v[98:101], v[144:147], v[228:231], v[98:101]
	v_mfma_f32_16x16x32_bf16 v[94:97], v[152:155], v[228:231], v[94:97]
	v_mfma_f32_16x16x32_bf16 v[82:85], v[144:147], v[236:239], v[82:85]
	v_mfma_f32_16x16x32_bf16 v[78:81], v[152:155], v[236:239], v[78:81]
	v_mfma_f32_16x16x32_bf16 v[118:121], v[156:159], v[190:193], v[118:121]
	v_mfma_f32_16x16x32_bf16 v[106:109], v[164:167], v[190:193], v[106:109]
	v_mfma_f32_16x16x32_bf16 v[102:105], v[156:159], v[212:215], v[102:105]
	v_mfma_f32_16x16x32_bf16 v[90:93], v[164:167], v[212:215], v[90:93]
	v_mfma_f32_16x16x32_bf16 v[86:89], v[156:159], v[224:227], v[86:89]
	v_mfma_f32_16x16x32_bf16 v[74:77], v[164:167], v[224:227], v[74:77]
	v_mfma_f32_16x16x32_bf16 v[70:73], v[156:159], v[232:235], v[70:73]
	v_mfma_f32_16x16x32_bf16 v[66:69], v[164:167], v[232:235], v[66:69]
	v_mfma_f32_16x16x32_bf16 v[118:121], v[160:163], v[194:197], v[118:121]
	v_mfma_f32_16x16x32_bf16 v[106:109], v[186:189], v[194:197], v[106:109]
	v_mfma_f32_16x16x32_bf16 v[102:105], v[160:163], v[220:223], v[102:105]
	v_mfma_f32_16x16x32_bf16 v[90:93], v[186:189], v[220:223], v[90:93]
	v_mfma_f32_16x16x32_bf16 v[86:89], v[160:163], v[228:231], v[86:89]
	v_mfma_f32_16x16x32_bf16 v[74:77], v[186:189], v[228:231], v[74:77]
	v_mfma_f32_16x16x32_bf16 v[70:73], v[160:163], v[236:239], v[70:73]
	v_mfma_f32_16x16x32_bf16 v[66:69], v[186:189], v[236:239], v[66:69]
	s_setprio 0
	s_barrier
; #define PG8_STAGE(bufoff, gbase, voff) do { _Pragma("unroll") for (int _i = 0; _i < 2; ++_i) \
;         __builtin_amdgcn_global_load_lds((const unsigned*)((const char*)(gbase) + (voff)[_i]), (PG8_LAS unsigned*)(lds + (bufoff) + ldsw + _i * 8192), 16, 0, 0); } while (0)
; #define PG8_LDA(dst, b, h) do { _Pragma("unroll") for (int m = 0; m < 4; ++m) _Pragma("unroll") for (int k = 0; k < 2; ++k) dst[m][k] = *(const PG8_LAS bf16x8*)(lds + PG8_SA(b, h) + aoff + m * 2048 + k * 1024); } while (0)
; #define PG8_MMA(ai, bj, At, Bt) do { __builtin_amdgcn_s_setprio(1); _Pragma("unroll") for (int m = 0; m < 4; ++m) _Pragma("unroll") for (int n = 0; n < 2; ++n) _Pragma("unroll") for (int k = 0; k < 2; ++k) \
;         acc[ai][bj][m][n] = __builtin_amdgcn_mfma_f32_16x16x32_bf16(Bt[n][k], At[m][k], acc[ai][bj][m][n], 0, 0, 0); __builtin_amdgcn_s_setprio(0); } while (0)
; #define PG8_WAIT_V(n) asm volatile("s_waitcnt vmcnt(" #n ")" ::: "memory")
; #define PG8_WAIT_L(n) asm volatile("s_waitcnt lgkmcnt(" #n ")" ::: "memory")
; #define PG8_BAR __builtin_amdgcn_s_barrier()
; #define PG8_SCHED __builtin_amdgcn_sched_barrier(0)
; template <class Epi, class Sched, bool ALIGN_EPI = false, bool SP2 = false>
; __device__ __forceinline__ void gemm_phase(PG8_LAS unsigned char* lds, const Gemm g, const Sched& S, const Epi& E, int tid_in) {
;     ...
;         for (int t = 0; t < nt; t += 2) {
;     ...
;             PG8_LDA(At, 1, 1); PG8_STAGE(PG8_SB(1, 0), b3, voffB); PG8_STAGE(PG8_SB(1, 1), b3 + hstep, voffB); PG8_STAGE(PG8_SA(1, 0), a3, voffA);
;             PG8_WAIT_V(8); PG8_WAIT_L(0); PG8_BAR; PG8_MMA(1, 0, At, B0); PG8_MMA(1, 1, At, B1); PG8_BAR; PG8_SCHED;
	s_add_i32 s24, s60, s4
	v_lshl_add_u64 v[168:169], v[168:169], 0, s[74:75]
	s_mov_b32 m0, s24
	ds_read_b128 v[190:193], v143 offset:49152
	ds_read_b128 v[194:197], v143 offset:50176
	ds_read_b128 v[212:215], v143 offset:51200
	ds_read_b128 v[220:223], v143 offset:52224
	ds_read_b128 v[224:227], v143 offset:53248
	ds_read_b128 v[228:231], v143 offset:54272
	ds_read_b128 v[232:235], v143 offset:55296
	ds_read_b128 v[236:239], v143 offset:56320
	global_load_lds_dwordx4 v[168:169], off
	s_add_i32 m0, s24, 0x2000
	s_add_u32 s24, s28, 0x80080
	v_lshl_add_u64 v[168:169], v[216:217], 0, s[74:75]
	s_addc_u32 s25, s29, 0
	s_add_i32 s28, s61, s4
	global_load_lds_dwordx4 v[168:169], off
	v_lshl_add_u64 v[168:169], s[24:25], 0, v[32:33]
	s_mov_b32 m0, s28
	s_nop 0
	global_load_lds_dwordx4 v[168:169], off
	v_lshl_add_u64 v[168:169], s[24:25], 0, v[130:131]
	s_add_i32 m0, s28, 0x2000
	s_nop 0
	global_load_lds_dwordx4 v[168:169], off
	v_lshl_add_u64 v[168:169], v[240:241], 0, s[74:75]
	s_mov_b32 m0, s49
	s_nop 0
	global_load_lds_dwordx4 v[168:169], off
	v_lshl_add_u64 v[168:169], v[242:243], 0, s[74:75]
	s_mov_b32 m0, s51
	s_nop 0
	global_load_lds_dwordx4 v[168:169], off
	s_waitcnt vmcnt(8)
	s_waitcnt lgkmcnt(0)
	s_setprio 1
	s_barrier
	v_mfma_f32_16x16x32_bf16 v[62:65], v[136:139], v[190:193], v[62:65]
	v_mfma_f32_16x16x32_bf16 v[58:61], v[148:151], v[190:193], v[58:61]
	v_mfma_f32_16x16x32_bf16 v[50:53], v[136:139], v[212:215], v[50:53]
	v_mfma_f32_16x16x32_bf16 v[46:49], v[148:151], v[212:215], v[46:49]
	v_mfma_f32_16x16x32_bf16 v[34:37], v[136:139], v[224:227], v[34:37]
	v_mfma_f32_16x16x32_bf16 v[28:31], v[148:151], v[224:227], v[28:31]
	v_mfma_f32_16x16x32_bf16 v[16:19], v[136:139], v[232:235], v[16:19]
	v_mfma_f32_16x16x32_bf16 v[12:15], v[148:151], v[232:235], v[12:15]
	v_mfma_f32_16x16x32_bf16 v[62:65], v[144:147], v[194:197], v[62:65]
	v_mfma_f32_16x16x32_bf16 v[58:61], v[152:155], v[194:197], v[58:61]
	v_mfma_f32_16x16x32_bf16 v[50:53], v[144:147], v[220:223], v[50:53]
	v_mfma_f32_16x16x32_bf16 v[46:49], v[152:155], v[220:223], v[46:49]
	v_mfma_f32_16x16x32_bf16 v[34:37], v[144:147], v[228:231], v[34:37]
	v_mfma_f32_16x16x32_bf16 v[28:31], v[152:155], v[228:231], v[28:31]
	v_mfma_f32_16x16x32_bf16 v[16:19], v[144:147], v[236:239], v[16:19]
	v_mfma_f32_16x16x32_bf16 v[12:15], v[152:155], v[236:239], v[12:15]
	v_mfma_f32_16x16x32_bf16 v[54:57], v[156:159], v[190:193], v[54:57]
	v_mfma_f32_16x16x32_bf16 v[42:45], v[164:167], v[190:193], v[42:45]
	v_mfma_f32_16x16x32_bf16 v[38:41], v[156:159], v[212:215], v[38:41]
	v_mfma_f32_16x16x32_bf16 v[24:27], v[164:167], v[212:215], v[24:27]
	v_mfma_f32_16x16x32_bf16 v[20:23], v[156:159], v[224:227], v[20:23]
	v_mfma_f32_16x16x32_bf16 v[8:11], v[164:167], v[224:227], v[8:11]
	v_mfma_f32_16x16x32_bf16 v[4:7], v[156:159], v[232:235], v[4:7]
	v_mfma_f32_16x16x32_bf16 v[0:3], v[164:167], v[232:235], v[0:3]
	v_mfma_f32_16x16x32_bf16 v[54:57], v[160:163], v[194:197], v[54:57]
	v_mfma_f32_16x16x32_bf16 v[42:45], v[186:189], v[194:197], v[42:45]
	v_mfma_f32_16x16x32_bf16 v[38:41], v[160:163], v[220:223], v[38:41]
	v_mfma_f32_16x16x32_bf16 v[24:27], v[186:189], v[220:223], v[24:27]
	v_mfma_f32_16x16x32_bf16 v[20:23], v[160:163], v[228:231], v[20:23]
	v_mfma_f32_16x16x32_bf16 v[8:11], v[186:189], v[228:231], v[8:11]
	v_mfma_f32_16x16x32_bf16 v[4:7], v[160:163], v[236:239], v[4:7]
	v_mfma_f32_16x16x32_bf16 v[0:3], v[186:189], v[236:239], v[0:3]
	s_setprio 0
	s_barrier
	s_add_i32 s59, s59, 2
	s_add_u32 s47, s47, 0x100
	s_addc_u32 s58, s58, 0
	s_cmp_gt_u32 s59, 29
	s_mov_b64 s[24:25], s[26:27]
	s_cbranch_scc0 .LBB0_349
	s_and_b64 vcc, exec, s[14:15]
	s_cbranch_vccz .LBB0_352
	s_barrier

; #define PG8_STAGE(bufoff, gbase, voff) do { _Pragma("unroll") for (int _i = 0; _i < 2; ++_i) \
;         __builtin_amdgcn_global_load_lds((const unsigned*)((const char*)(gbase) + (voff)[_i]), (PG8_LAS unsigned*)(lds + (bufoff) + ldsw + _i * 8192), 16, 0, 0); } while (0)
; #define PG8_LDA(dst, b, h) do { _Pragma("unroll") for (int m = 0; m < 4; ++m) _Pragma("unroll") for (int k = 0; k < 2; ++k) dst[m][k] = *(const PG8_LAS bf16x8*)(lds + PG8_SA(b, h) + aoff + m * 2048 + k * 1024); } while (0)
; #define PG8_LDB(dst, b, h) do { _Pragma("unroll") for (int n = 0; n < 2; ++n) _Pragma("unroll") for (int k = 0; k < 2; ++k) dst[n][k] = *(const PG8_LAS bf16x8*)(lds + PG8_SB(b, h) + boff + n * 2048 + k * 1024); } while (0)
; #define PG8_MMA(ai, bj, At, Bt) do { __builtin_amdgcn_s_setprio(1); _Pragma("unroll") for (int m = 0; m < 4; ++m) _Pragma("unroll") for (int n = 0; n < 2; ++n) _Pragma("unroll") for (int k = 0; k < 2; ++k) \
;         acc[ai][bj][m][n] = __builtin_amdgcn_mfma_f32_16x16x32_bf16(Bt[n][k], At[m][k], acc[ai][bj][m][n], 0, 0, 0); __builtin_amdgcn_s_setprio(0); } while (0)
; #define PG8_WAIT_V(n) asm volatile("s_waitcnt vmcnt(" #n ")" ::: "memory")
; #define PG8_WAIT_L(n) asm volatile("s_waitcnt lgkmcnt(" #n ")" ::: "memory")
; template <class Epi, class Sched, bool ALIGN_EPI = false, bool SP2 = false>
; __device__ __forceinline__ void gemm_phase(PG8_LAS unsigned char* lds, const Gemm g, const Sched& S, const Epi& E, int tid_in) {
;     ...
;             const bool last = (t == nt - 2);
;             const char* a1 = cA + (size_t)(t + 1) * kstep;
;             const char* a2 = last ? nA : cA + (size_t)(t + 2) * kstep; const char* b2 = last ? nB : cB + (size_t)(t + 2) * kstep;
;             const char* a3 = a2 + kstep; const char* b3 = b2 + kstep;
;             if (last && has_next) S.a_ready(nxt);
;             if constexpr (SP2) {
;             PG8_LDB(B0, 0, 0); PG8_LDB(B1, 0, 1); PG8_SCHED; PG8_LDA(At, 0, 0); PG8_STAGE(PG8_SA(1, 1), a1 + hstep, voffA);
;             PG8_WAIT_V(8); PG8_WAIT_L(0); PG8_BAR; PG8_MMA(0, 0, At, B0); PG8_MMA(0, 1, At, B1); PG8_BAR; PG8_SCHED;
;             PG8_LDA(At, 0, 1); PG8_STAGE(PG8_SB(0, 0), b2, voffB); PG8_STAGE(PG8_SB(0, 1), b2 + hstep, voffB); PG8_STAGE(PG8_SA(0, 0), a2, voffA);
;             PG8_WAIT_V(8); PG8_WAIT_L(0); PG8_BAR; PG8_MMA(1, 0, At, B0); PG8_MMA(1, 1, At, B1); PG8_BAR; PG8_SCHED;
.LBB0_479:
	s_add_u32 s16, s56, 0xfff80080
	s_addc_u32 s17, s57, -1
	s_add_i32 s18, 0, 0x10000
	s_cmp_eq_u32 s82, 28
	s_cselect_b32 s63, s71, s17
	s_cselect_b32 s62, vcc_lo, s16
	s_cselect_b32 s61, s59, s77
	s_cselect_b32 s60, vcc_hi, s47
	s_add_i32 s19, 0, 0x14000
	v_add_u32_e32 v78, s18, v172
	v_add_u32_e32 v102, s19, v172
	ds_read_b128 v[66:69], v78
	ds_read_b128 v[70:73], v78 offset:1024
	ds_read_b128 v[74:77], v78 offset:2048
	ds_read_b128 v[78:81], v78 offset:3072
	ds_read_b128 v[86:89], v102
	ds_read_b128 v[90:93], v102 offset:1024
	ds_read_b128 v[94:97], v102 offset:2048
	ds_read_b128 v[102:105], v102 offset:3072
	v_lshl_add_u64 v[196:197], s[56:57], 0, v[192:193]
	s_add_i32 m0, s68, 0xc000
	ds_read_b128 v[162:165], v217
	ds_read_b128 v[166:169], v217 offset:1024
	ds_read_b128 v[220:223], v217 offset:2048
	ds_read_b128 v[224:227], v217 offset:3072
	ds_read_b128 v[228:231], v217 offset:4096
	ds_read_b128 v[232:235], v217 offset:5120
	ds_read_b128 v[236:239], v217 offset:6144
	ds_read_b128 v[240:243], v217 offset:7168
	global_load_lds_dwordx4 v[196:197], off
	v_lshl_add_u64 v[196:197], s[56:57], 0, v[194:195]
	s_add_i32 m0, s68, 0xe000
	s_nop 0
	global_load_lds_dwordx4 v[196:197], off
	s_waitcnt vmcnt(8)
	s_waitcnt lgkmcnt(0)
	s_setprio 1
	s_barrier
	v_mfma_f32_16x16x32_bf16 v[150:153], v[66:69], v[162:165], v[150:153]
	v_mfma_f32_16x16x32_bf16 v[146:149], v[74:77], v[162:165], v[146:149]
	v_mfma_f32_16x16x32_bf16 v[138:141], v[66:69], v[220:223], v[138:141]
	v_mfma_f32_16x16x32_bf16 v[130:133], v[74:77], v[220:223], v[130:133]
	v_mfma_f32_16x16x32_bf16 v[122:125], v[66:69], v[228:231], v[122:125]
	v_mfma_f32_16x16x32_bf16 v[110:113], v[74:77], v[228:231], v[110:113]
	v_mfma_f32_16x16x32_bf16 v[114:117], v[66:69], v[236:239], v[114:117]
	v_mfma_f32_16x16x32_bf16 v[98:101], v[74:77], v[236:239], v[98:101]
	v_mfma_f32_16x16x32_bf16 v[150:153], v[70:73], v[166:169], v[150:153]
	v_mfma_f32_16x16x32_bf16 v[146:149], v[78:81], v[166:169], v[146:149]
	v_mfma_f32_16x16x32_bf16 v[138:141], v[70:73], v[224:227], v[138:141]
	v_mfma_f32_16x16x32_bf16 v[130:133], v[78:81], v[224:227], v[130:133]
	v_mfma_f32_16x16x32_bf16 v[122:125], v[70:73], v[232:235], v[122:125]
	v_mfma_f32_16x16x32_bf16 v[110:113], v[78:81], v[232:235], v[110:113]
	v_mfma_f32_16x16x32_bf16 v[114:117], v[70:73], v[240:243], v[114:117]
	v_mfma_f32_16x16x32_bf16 v[98:101], v[78:81], v[240:243], v[98:101]
	v_mfma_f32_16x16x32_bf16 v[158:161], v[86:89], v[162:165], v[158:161]
	v_mfma_f32_16x16x32_bf16 v[154:157], v[94:97], v[162:165], v[154:157]
	v_mfma_f32_16x16x32_bf16 v[142:145], v[86:89], v[220:223], v[142:145]
	v_mfma_f32_16x16x32_bf16 v[134:137], v[94:97], v[220:223], v[134:137]
	v_mfma_f32_16x16x32_bf16 v[126:129], v[86:89], v[228:231], v[126:129]
	v_mfma_f32_16x16x32_bf16 v[118:121], v[94:97], v[228:231], v[118:121]
	v_mfma_f32_16x16x32_bf16 v[106:109], v[86:89], v[236:239], v[106:109]
	v_mfma_f32_16x16x32_bf16 v[82:85], v[94:97], v[236:239], v[82:85]
	v_mfma_f32_16x16x32_bf16 v[158:161], v[90:93], v[166:169], v[158:161]
	v_mfma_f32_16x16x32_bf16 v[154:157], v[102:105], v[166:169], v[154:157]
	v_mfma_f32_16x16x32_bf16 v[142:145], v[90:93], v[224:227], v[142:145]
	v_mfma_f32_16x16x32_bf16 v[134:137], v[102:105], v[224:227], v[134:137]
	v_mfma_f32_16x16x32_bf16 v[126:129], v[90:93], v[232:235], v[126:129]
	v_mfma_f32_16x16x32_bf16 v[118:121], v[102:105], v[232:235], v[118:121]
	v_mfma_f32_16x16x32_bf16 v[106:109], v[90:93], v[240:243], v[106:109]
	v_mfma_f32_16x16x32_bf16 v[82:85], v[102:105], v[240:243], v[82:85]
	s_setprio 0
	s_barrier
	s_add_i32 s16, s18, s67
	v_lshl_add_u64 v[196:197], s[60:61], 0, v[32:33]
	s_mov_b32 m0, s16
	ds_read_b128 v[162:165], v217 offset:16384
	ds_read_b128 v[166:169], v217 offset:17408
	ds_read_b128 v[220:223], v217 offset:18432
	ds_read_b128 v[224:227], v217 offset:19456
	ds_read_b128 v[228:231], v217 offset:20480
	ds_read_b128 v[232:235], v217 offset:21504
	ds_read_b128 v[236:239], v217 offset:22528
	ds_read_b128 v[240:243], v217 offset:23552
	global_load_lds_dwordx4 v[196:197], off
	s_add_i32 m0, s16, 0x2000
	s_add_u32 s16, s60, 0x80000
	v_lshl_add_u64 v[244:245], s[60:61], 0, v[186:187]
	s_addc_u32 s17, s61, 0
	s_add_i32 s18, s19, s67
	global_load_lds_dwordx4 v[244:245], off
	v_lshl_add_u64 v[246:247], s[16:17], 0, v[32:33]
	s_mov_b32 m0, s18
	v_lshl_add_u64 v[248:249], s[62:63], 0, v[188:189]
	global_load_lds_dwordx4 v[246:247], off
	v_lshl_add_u64 v[246:247], s[16:17], 0, v[186:187]
	s_add_i32 m0, s18, 0x2000
	s_nop 0
	global_load_lds_dwordx4 v[246:247], off
	v_lshl_add_u64 v[246:247], s[62:63], 0, v[190:191]
	s_mov_b32 m0, s68
	s_nop 0
	global_load_lds_dwordx4 v[246:247], off
	s_mov_b32 m0, s14
	s_nop 0
	global_load_lds_dwordx4 v[248:249], off
	s_waitcnt vmcnt(8)
	s_waitcnt lgkmcnt(0)
	s_setprio 1
	s_barrier
; #define PG8_STAGE(bufoff, gbase, voff) do { _Pragma("unroll") for (int _i = 0; _i < 2; ++_i) \
;         __builtin_amdgcn_global_load_lds((const unsigned*)((const char*)(gbase) + (voff)[_i]), (PG8_LAS unsigned*)(lds + (bufoff) + ldsw + _i * 8192), 16, 0, 0); } while (0)
; #define PG8_LDA(dst, b, h) do { _Pragma("unroll") for (int m = 0; m < 4; ++m) _Pragma("unroll") for (int k = 0; k < 2; ++k) dst[m][k] = *(const PG8_LAS bf16x8*)(lds + PG8_SA(b, h) + aoff + m * 2048 + k * 1024); } while (0)
; #define PG8_LDB(dst, b, h) do { _Pragma("unroll") for (int n = 0; n < 2; ++n) _Pragma("unroll") for (int k = 0; k < 2; ++k) dst[n][k] = *(const PG8_LAS bf16x8*)(lds + PG8_SB(b, h) + boff + n * 2048 + k * 1024); } while (0)
; #define PG8_MMA(ai, bj, At, Bt) do { __builtin_amdgcn_s_setprio(1); _Pragma("unroll") for (int m = 0; m < 4; ++m) _Pragma("unroll") for (int n = 0; n < 2; ++n) _Pragma("unroll") for (int k = 0; k < 2; ++k) \
;         acc[ai][bj][m][n] = __builtin_amdgcn_mfma_f32_16x16x32_bf16(Bt[n][k], At[m][k], acc[ai][bj][m][n], 0, 0, 0); __builtin_amdgcn_s_setprio(0); } while (0)
; #define PG8_WAIT_V(n) asm volatile("s_waitcnt vmcnt(" #n ")" ::: "memory")
; #define PG8_WAIT_L(n) asm volatile("s_waitcnt lgkmcnt(" #n ")" ::: "memory")
; #define PG8_BAR __builtin_amdgcn_s_barrier()
; #define PG8_SCHED __builtin_amdgcn_sched_barrier(0)
; template <class Epi, class Sched, bool ALIGN_EPI = false, bool SP2 = false>
; __device__ __forceinline__ void gemm_phase(PG8_LAS unsigned char* lds, const Gemm g, const Sched& S, const Epi& E, int tid_in) {
;     ...
;             PG8_WAIT_V(8); PG8_WAIT_L(0); PG8_BAR; PG8_MMA(1, 0, At, B0); PG8_MMA(1, 1, At, B1); PG8_BAR; PG8_SCHED;
;             PG8_LDB(B0, 1, 0); PG8_LDB(B1, 1, 1); PG8_SCHED; PG8_LDA(At, 1, 0); PG8_STAGE(PG8_SA(0, 1), a2 + hstep, voffA);
;             PG8_WAIT_V(8); PG8_WAIT_L(0); PG8_BAR; PG8_MMA(0, 0, At, B0); PG8_MMA(0, 1, At, B1); PG8_BAR; PG8_SCHED;
	v_mfma_f32_16x16x32_bf16 v[54:57], v[66:69], v[162:165], v[54:57]
	v_mfma_f32_16x16x32_bf16 v[50:53], v[74:77], v[162:165], v[50:53]
	v_mfma_f32_16x16x32_bf16 v[42:45], v[66:69], v[220:223], v[42:45]
	v_mfma_f32_16x16x32_bf16 v[34:37], v[74:77], v[220:223], v[34:37]
	v_mfma_f32_16x16x32_bf16 v[24:27], v[66:69], v[228:231], v[24:27]
	v_mfma_f32_16x16x32_bf16 v[12:15], v[74:77], v[228:231], v[12:15]
	v_mfma_f32_16x16x32_bf16 v[16:19], v[66:69], v[236:239], v[16:19]
	v_mfma_f32_16x16x32_bf16 v[4:7], v[74:77], v[236:239], v[4:7]
	v_mfma_f32_16x16x32_bf16 v[54:57], v[70:73], v[166:169], v[54:57]
	v_mfma_f32_16x16x32_bf16 v[50:53], v[78:81], v[166:169], v[50:53]
	v_mfma_f32_16x16x32_bf16 v[42:45], v[70:73], v[224:227], v[42:45]
	v_mfma_f32_16x16x32_bf16 v[34:37], v[78:81], v[224:227], v[34:37]
	v_mfma_f32_16x16x32_bf16 v[24:27], v[70:73], v[232:235], v[24:27]
	v_mfma_f32_16x16x32_bf16 v[12:15], v[78:81], v[232:235], v[12:15]
	v_mfma_f32_16x16x32_bf16 v[16:19], v[70:73], v[240:243], v[16:19]
	v_mfma_f32_16x16x32_bf16 v[4:7], v[78:81], v[240:243], v[4:7]
	v_mfma_f32_16x16x32_bf16 v[62:65], v[86:89], v[162:165], v[62:65]
	v_mfma_f32_16x16x32_bf16 v[58:61], v[94:97], v[162:165], v[58:61]
	v_mfma_f32_16x16x32_bf16 v[46:49], v[86:89], v[220:223], v[46:49]
	v_mfma_f32_16x16x32_bf16 v[38:41], v[94:97], v[220:223], v[38:41]
	v_mfma_f32_16x16x32_bf16 v[28:31], v[86:89], v[228:231], v[28:31]
	v_mfma_f32_16x16x32_bf16 v[20:23], v[94:97], v[228:231], v[20:23]
	v_mfma_f32_16x16x32_bf16 v[8:11], v[86:89], v[236:239], v[8:11]
	v_mfma_f32_16x16x32_bf16 v[0:3], v[94:97], v[236:239], v[0:3]
	v_mfma_f32_16x16x32_bf16 v[62:65], v[90:93], v[166:169], v[62:65]
	v_mfma_f32_16x16x32_bf16 v[58:61], v[102:105], v[166:169], v[58:61]
	v_mfma_f32_16x16x32_bf16 v[46:49], v[90:93], v[224:227], v[46:49]
	v_mfma_f32_16x16x32_bf16 v[38:41], v[102:105], v[224:227], v[38:41]
	v_mfma_f32_16x16x32_bf16 v[28:31], v[90:93], v[232:235], v[28:31]
	v_mfma_f32_16x16x32_bf16 v[20:23], v[102:105], v[232:235], v[20:23]
	v_mfma_f32_16x16x32_bf16 v[8:11], v[90:93], v[240:243], v[8:11]
	v_mfma_f32_16x16x32_bf16 v[0:3], v[102:105], v[240:243], v[0:3]
	s_setprio 0
	s_barrier
	s_add_i32 s18, 0, 0x18000
	s_add_i32 s19, 0, 0x1c000
	v_add_u32_e32 v78, s18, v172
	v_add_u32_e32 v102, s19, v172
	ds_read_b128 v[66:69], v78
	ds_read_b128 v[70:73], v78 offset:1024
	ds_read_b128 v[74:77], v78 offset:2048
	ds_read_b128 v[78:81], v78 offset:3072
	ds_read_b128 v[86:89], v102
	ds_read_b128 v[90:93], v102 offset:1024
	ds_read_b128 v[94:97], v102 offset:2048
	ds_read_b128 v[102:105], v102 offset:3072
	s_add_u32 s16, s62, 0x80000
	s_addc_u32 s17, s63, 0
	s_mov_b32 m0, s15
	v_lshl_add_u64 v[250:251], s[16:17], 0, v[190:191]
	ds_read_b128 v[162:165], v217 offset:32768
	ds_read_b128 v[166:169], v217 offset:33792
	ds_read_b128 v[220:223], v217 offset:34816
	ds_read_b128 v[224:227], v217 offset:35840
	ds_read_b128 v[228:231], v217 offset:36864
	ds_read_b128 v[232:235], v217 offset:37888
	ds_read_b128 v[236:239], v217 offset:38912
	ds_read_b128 v[240:243], v217 offset:39936
	global_load_lds_dwordx4 v[250:251], off
	v_lshl_add_u64 v[250:251], s[16:17], 0, v[188:189]
	s_mov_b32 m0, s4
	s_nop 0
	global_load_lds_dwordx4 v[250:251], off
	s_waitcnt vmcnt(8)
	s_waitcnt lgkmcnt(0)
	s_setprio 1
	s_barrier
	v_mfma_f32_16x16x32_bf16 v[150:153], v[66:69], v[162:165], v[150:153]
	v_mfma_f32_16x16x32_bf16 v[146:149], v[74:77], v[162:165], v[146:149]
	v_mfma_f32_16x16x32_bf16 v[138:141], v[66:69], v[220:223], v[138:141]
	v_mfma_f32_16x16x32_bf16 v[130:133], v[74:77], v[220:223], v[130:133]
	v_mfma_f32_16x16x32_bf16 v[122:125], v[66:69], v[228:231], v[122:125]
	v_mfma_f32_16x16x32_bf16 v[110:113], v[74:77], v[228:231], v[110:113]
	v_mfma_f32_16x16x32_bf16 v[114:117], v[66:69], v[236:239], v[114:117]
	v_mfma_f32_16x16x32_bf16 v[98:101], v[74:77], v[236:239], v[98:101]
	v_mfma_f32_16x16x32_bf16 v[150:153], v[70:73], v[166:169], v[150:153]
	v_mfma_f32_16x16x32_bf16 v[146:149], v[78:81], v[166:169], v[146:149]
	v_mfma_f32_16x16x32_bf16 v[138:141], v[70:73], v[224:227], v[138:141]
	v_mfma_f32_16x16x32_bf16 v[130:133], v[78:81], v[224:227], v[130:133]
	v_mfma_f32_16x16x32_bf16 v[122:125], v[70:73], v[232:235], v[122:125]
	v_mfma_f32_16x16x32_bf16 v[110:113], v[78:81], v[232:235], v[110:113]
	v_mfma_f32_16x16x32_bf16 v[114:117], v[70:73], v[240:243], v[114:117]
	v_mfma_f32_16x16x32_bf16 v[98:101], v[78:81], v[240:243], v[98:101]
	v_mfma_f32_16x16x32_bf16 v[158:161], v[86:89], v[162:165], v[158:161]
	v_mfma_f32_16x16x32_bf16 v[154:157], v[94:97], v[162:165], v[154:157]
	v_mfma_f32_16x16x32_bf16 v[142:145], v[86:89], v[220:223], v[142:145]
	v_mfma_f32_16x16x32_bf16 v[134:137], v[94:97], v[220:223], v[134:137]
	v_mfma_f32_16x16x32_bf16 v[126:129], v[86:89], v[228:231], v[126:129]
	v_mfma_f32_16x16x32_bf16 v[118:121], v[94:97], v[228:231], v[118:121]
	v_mfma_f32_16x16x32_bf16 v[106:109], v[86:89], v[236:239], v[106:109]
	v_mfma_f32_16x16x32_bf16 v[82:85], v[94:97], v[236:239], v[82:85]
	v_mfma_f32_16x16x32_bf16 v[158:161], v[90:93], v[166:169], v[158:161]
	v_mfma_f32_16x16x32_bf16 v[154:157], v[102:105], v[166:169], v[154:157]
	v_mfma_f32_16x16x32_bf16 v[142:145], v[90:93], v[224:227], v[142:145]
	v_mfma_f32_16x16x32_bf16 v[134:137], v[102:105], v[224:227], v[134:137]
	v_mfma_f32_16x16x32_bf16 v[126:129], v[90:93], v[232:235], v[126:129]
	v_mfma_f32_16x16x32_bf16 v[118:121], v[102:105], v[232:235], v[118:121]
	v_mfma_f32_16x16x32_bf16 v[106:109], v[90:93], v[240:243], v[106:109]
	v_mfma_f32_16x16x32_bf16 v[82:85], v[102:105], v[240:243], v[82:85]
	s_setprio 0
	s_barrier
; #define PG8_STAGE(bufoff, gbase, voff) do { _Pragma("unroll") for (int _i = 0; _i < 2; ++_i) \
;         __builtin_amdgcn_global_load_lds((const unsigned*)((const char*)(gbase) + (voff)[_i]), (PG8_LAS unsigned*)(lds + (bufoff) + ldsw + _i * 8192), 16, 0, 0); } while (0)
; #define PG8_LDA(dst, b, h) do { _Pragma("unroll") for (int m = 0; m < 4; ++m) _Pragma("unroll") for (int k = 0; k < 2; ++k) dst[m][k] = *(const PG8_LAS bf16x8*)(lds + PG8_SA(b, h) + aoff + m * 2048 + k * 1024); } while (0)
; #define PG8_MMA(ai, bj, At, Bt) do { __builtin_amdgcn_s_setprio(1); _Pragma("unroll") for (int m = 0; m < 4; ++m) _Pragma("unroll") for (int n = 0; n < 2; ++n) _Pragma("unroll") for (int k = 0; k < 2; ++k) \
;         acc[ai][bj][m][n] = __builtin_amdgcn_mfma_f32_16x16x32_bf16(Bt[n][k], At[m][k], acc[ai][bj][m][n], 0, 0, 0); __builtin_amdgcn_s_setprio(0); } while (0)
; #define PG8_WAIT_V(n) asm volatile("s_waitcnt vmcnt(" #n ")" ::: "memory")
; #define PG8_WAIT_L(n) asm volatile("s_waitcnt lgkmcnt(" #n ")" ::: "memory")
; #define PG8_BAR __builtin_amdgcn_s_barrier()
; #define PG8_SCHED __builtin_amdgcn_sched_barrier(0)
; template <class Epi, class Sched, bool ALIGN_EPI = false, bool SP2 = false>
; __device__ __forceinline__ void gemm_phase(PG8_LAS unsigned char* lds, const Gemm g, const Sched& S, const Epi& E, int tid_in) {
;     ...
;         for (int t = 0; t < nt; t += 2) {
;     ...
;             PG8_LDA(At, 1, 1); PG8_STAGE(PG8_SB(1, 0), b3, voffB); PG8_STAGE(PG8_SB(1, 1), b3 + hstep, voffB); PG8_STAGE(PG8_SA(1, 0), a3, voffA);
;             PG8_WAIT_V(8); PG8_WAIT_L(0); PG8_BAR; PG8_MMA(1, 0, At, B0); PG8_MMA(1, 1, At, B1); PG8_BAR; PG8_SCHED;
	s_add_i32 s16, s18, s67
	v_lshl_add_u64 v[196:197], v[196:197], 0, s[74:75]
	s_mov_b32 m0, s16
	ds_read_b128 v[162:165], v217 offset:49152
	ds_read_b128 v[166:169], v217 offset:50176
	ds_read_b128 v[220:223], v217 offset:51200
	ds_read_b128 v[224:227], v217 offset:52224
	ds_read_b128 v[228:231], v217 offset:53248
	ds_read_b128 v[232:235], v217 offset:54272
	ds_read_b128 v[236:239], v217 offset:55296
	ds_read_b128 v[240:243], v217 offset:56320
	global_load_lds_dwordx4 v[196:197], off
	s_add_i32 m0, s16, 0x2000
	s_add_u32 s16, s60, 0x80080
	v_lshl_add_u64 v[196:197], v[244:245], 0, s[74:75]
	s_addc_u32 s17, s61, 0
	s_add_i32 s18, s19, s67
	global_load_lds_dwordx4 v[196:197], off
	v_lshl_add_u64 v[196:197], s[16:17], 0, v[32:33]
	s_mov_b32 m0, s18
	s_nop 0
	global_load_lds_dwordx4 v[196:197], off
	v_lshl_add_u64 v[196:197], s[16:17], 0, v[186:187]
	s_add_i32 m0, s18, 0x2000
	s_nop 0
	global_load_lds_dwordx4 v[196:197], off
	v_lshl_add_u64 v[196:197], v[246:247], 0, s[74:75]
	s_mov_b32 m0, s85
	s_nop 0
	global_load_lds_dwordx4 v[196:197], off
	v_lshl_add_u64 v[196:197], v[248:249], 0, s[74:75]
	s_mov_b32 m0, s80
	s_nop 0
	global_load_lds_dwordx4 v[196:197], off
	s_waitcnt vmcnt(8)
	s_waitcnt lgkmcnt(0)
	s_setprio 1
	s_barrier
	v_mfma_f32_16x16x32_bf16 v[54:57], v[66:69], v[162:165], v[54:57]
	v_mfma_f32_16x16x32_bf16 v[50:53], v[74:77], v[162:165], v[50:53]
	v_mfma_f32_16x16x32_bf16 v[42:45], v[66:69], v[220:223], v[42:45]
	v_mfma_f32_16x16x32_bf16 v[34:37], v[74:77], v[220:223], v[34:37]
	v_mfma_f32_16x16x32_bf16 v[24:27], v[66:69], v[228:231], v[24:27]
	v_mfma_f32_16x16x32_bf16 v[12:15], v[74:77], v[228:231], v[12:15]
	v_mfma_f32_16x16x32_bf16 v[16:19], v[66:69], v[236:239], v[16:19]
	v_mfma_f32_16x16x32_bf16 v[4:7], v[74:77], v[236:239], v[4:7]
	v_mfma_f32_16x16x32_bf16 v[54:57], v[70:73], v[166:169], v[54:57]
	v_mfma_f32_16x16x32_bf16 v[50:53], v[78:81], v[166:169], v[50:53]
	v_mfma_f32_16x16x32_bf16 v[42:45], v[70:73], v[224:227], v[42:45]
	v_mfma_f32_16x16x32_bf16 v[34:37], v[78:81], v[224:227], v[34:37]
	v_mfma_f32_16x16x32_bf16 v[24:27], v[70:73], v[232:235], v[24:27]
	v_mfma_f32_16x16x32_bf16 v[12:15], v[78:81], v[232:235], v[12:15]
	v_mfma_f32_16x16x32_bf16 v[16:19], v[70:73], v[240:243], v[16:19]
	v_mfma_f32_16x16x32_bf16 v[4:7], v[78:81], v[240:243], v[4:7]
	v_mfma_f32_16x16x32_bf16 v[62:65], v[86:89], v[162:165], v[62:65]
	v_mfma_f32_16x16x32_bf16 v[58:61], v[94:97], v[162:165], v[58:61]
	v_mfma_f32_16x16x32_bf16 v[46:49], v[86:89], v[220:223], v[46:49]
	v_mfma_f32_16x16x32_bf16 v[38:41], v[94:97], v[220:223], v[38:41]
	v_mfma_f32_16x16x32_bf16 v[28:31], v[86:89], v[228:231], v[28:31]
	v_mfma_f32_16x16x32_bf16 v[20:23], v[94:97], v[228:231], v[20:23]
	v_mfma_f32_16x16x32_bf16 v[8:11], v[86:89], v[236:239], v[8:11]
	v_mfma_f32_16x16x32_bf16 v[0:3], v[94:97], v[236:239], v[0:3]
	v_mfma_f32_16x16x32_bf16 v[62:65], v[90:93], v[166:169], v[62:65]
	v_mfma_f32_16x16x32_bf16 v[58:61], v[102:105], v[166:169], v[58:61]
	v_mfma_f32_16x16x32_bf16 v[46:49], v[90:93], v[224:227], v[46:49]
	v_mfma_f32_16x16x32_bf16 v[38:41], v[102:105], v[224:227], v[38:41]
	v_mfma_f32_16x16x32_bf16 v[28:31], v[90:93], v[232:235], v[28:31]
	v_mfma_f32_16x16x32_bf16 v[20:23], v[102:105], v[232:235], v[20:23]
	v_mfma_f32_16x16x32_bf16 v[8:11], v[90:93], v[240:243], v[8:11]
	v_mfma_f32_16x16x32_bf16 v[0:3], v[102:105], v[240:243], v[0:3]
	s_setprio 0
	s_barrier
	s_add_i32 s82, s82, 2
	s_add_u32 s56, s56, 0x100
	s_addc_u32 s57, s57, 0
	s_add_u32 s47, s47, 0x100
	s_addc_u32 s77, s77, 0
	s_cmp_gt_u32 s82, 29
	s_cbranch_scc0 .LBB0_479
	s_and_b64 vcc, exec, s[34:35]
	s_cbranch_vccz .LBB0_482
	s_barrier

; #define PG8_STAGE(bufoff, gbase, voff) do { _Pragma("unroll") for (int _i = 0; _i < 2; ++_i) \
;         __builtin_amdgcn_global_load_lds((const unsigned*)((const char*)(gbase) + (voff)[_i]), (PG8_LAS unsigned*)(lds + (bufoff) + ldsw + _i * 8192), 16, 0, 0); } while (0)
; #define PG8_LDA(dst, b, h) do { _Pragma("unroll") for (int m = 0; m < 4; ++m) _Pragma("unroll") for (int k = 0; k < 2; ++k) dst[m][k] = *(const PG8_LAS bf16x8*)(lds + PG8_SA(b, h) + aoff + m * 2048 + k * 1024); } while (0)
; #define PG8_LDB(dst, b, h) do { _Pragma("unroll") for (int n = 0; n < 2; ++n) _Pragma("unroll") for (int k = 0; k < 2; ++k) dst[n][k] = *(const PG8_LAS bf16x8*)(lds + PG8_SB(b, h) + boff + n * 2048 + k * 1024); } while (0)
; #define PG8_MMA(ai, bj, At, Bt) do { __builtin_amdgcn_s_setprio(1); _Pragma("unroll") for (int m = 0; m < 4; ++m) _Pragma("unroll") for (int n = 0; n < 2; ++n) _Pragma("unroll") for (int k = 0; k < 2; ++k) \
;         acc[ai][bj][m][n] = __builtin_amdgcn_mfma_f32_16x16x32_bf16(Bt[n][k], At[m][k], acc[ai][bj][m][n], 0, 0, 0); __builtin_amdgcn_s_setprio(0); } while (0)
; #define PG8_WAIT_V(n) asm volatile("s_waitcnt vmcnt(" #n ")" ::: "memory")
; #define PG8_WAIT_L(n) asm volatile("s_waitcnt lgkmcnt(" #n ")" ::: "memory")
; template <class Epi, class Sched, bool ALIGN_EPI = false, bool SP2 = false>
; __device__ __forceinline__ void gemm_phase(PG8_LAS unsigned char* lds, const Gemm g, const Sched& S, const Epi& E, int tid_in) {
;     ...
;             const bool last = (t == nt - 2);
;             const char* a1 = cA + (size_t)(t + 1) * kstep;
;             const char* a2 = last ? nA : cA + (size_t)(t + 2) * kstep; const char* b2 = last ? nB : cB + (size_t)(t + 2) * kstep;
;             const char* a3 = a2 + kstep; const char* b3 = b2 + kstep;
;             if (last && has_next) S.a_ready(nxt);
;             if constexpr (SP2) {
;             PG8_LDB(B0, 0, 0); PG8_LDB(B1, 0, 1); PG8_SCHED; PG8_LDA(At, 0, 0); PG8_STAGE(PG8_SA(1, 1), a1 + hstep, voffA);
;             PG8_WAIT_V(8); PG8_WAIT_L(0); PG8_BAR; PG8_MMA(0, 0, At, B0); PG8_MMA(0, 1, At, B1); PG8_BAR; PG8_SCHED;
;             PG8_LDA(At, 0, 1); PG8_STAGE(PG8_SB(0, 0), b2, voffB); PG8_STAGE(PG8_SB(0, 1), b2 + hstep, voffB); PG8_STAGE(PG8_SA(0, 0), a2, voffA);
;             PG8_WAIT_V(8); PG8_WAIT_L(0); PG8_BAR; PG8_MMA(1, 0, At, B0); PG8_MMA(1, 1, At, B1); PG8_BAR; PG8_SCHED;
.LBB0_625:
	s_add_u32 s26, s24, 0x100
	s_addc_u32 s27, s25, 0
	s_add_i32 s58, 0, 0x10000
	s_cmpk_eq_i32 s57, 0x54
	s_cselect_b32 s31, s7, s27
	s_cselect_b32 s30, s6, s26
	s_cselect_b32 s29, s23, s47
	s_cselect_b32 s28, s22, s45
	s_add_i32 s59, 0, 0x14000
	v_add_u32_e32 v152, s58, v141
	v_add_u32_e32 v168, s59, v141
	ds_read_b128 v[136:139], v152
	ds_read_b128 v[144:147], v152 offset:1024
	ds_read_b128 v[148:151], v152 offset:2048
	ds_read_b128 v[152:155], v152 offset:3072
	ds_read_b128 v[156:159], v168
	ds_read_b128 v[160:163], v168 offset:1024
	ds_read_b128 v[164:167], v168 offset:2048
	ds_read_b128 v[186:189], v168 offset:3072
	v_lshl_add_u64 v[168:169], s[24:25], 0, v[132:133]
	s_add_i32 m0, s38, 0xc000
	ds_read_b128 v[190:193], v143
	ds_read_b128 v[194:197], v143 offset:1024
	ds_read_b128 v[212:215], v143 offset:2048
	ds_read_b128 v[220:223], v143 offset:3072
	ds_read_b128 v[224:227], v143 offset:4096
	ds_read_b128 v[228:231], v143 offset:5120
	ds_read_b128 v[232:235], v143 offset:6144
	ds_read_b128 v[236:239], v143 offset:7168
	global_load_lds_dwordx4 v[168:169], off
	v_lshl_add_u64 v[168:169], s[24:25], 0, v[134:135]
	s_add_i32 m0, s38, 0xe000
	s_nop 0
	global_load_lds_dwordx4 v[168:169], off
	s_waitcnt vmcnt(8)
	s_waitcnt lgkmcnt(0)
	s_setprio 1
	s_barrier
	v_mfma_f32_16x16x32_bf16 v[126:129], v[136:139], v[190:193], v[126:129]
	v_mfma_f32_16x16x32_bf16 v[122:125], v[148:151], v[190:193], v[122:125]
	v_mfma_f32_16x16x32_bf16 v[114:117], v[136:139], v[212:215], v[114:117]
	v_mfma_f32_16x16x32_bf16 v[110:113], v[148:151], v[212:215], v[110:113]
	v_mfma_f32_16x16x32_bf16 v[98:101], v[136:139], v[224:227], v[98:101]
	v_mfma_f32_16x16x32_bf16 v[94:97], v[148:151], v[224:227], v[94:97]
	v_mfma_f32_16x16x32_bf16 v[82:85], v[136:139], v[232:235], v[82:85]
	v_mfma_f32_16x16x32_bf16 v[78:81], v[148:151], v[232:235], v[78:81]
	v_mfma_f32_16x16x32_bf16 v[126:129], v[144:147], v[194:197], v[126:129]
	v_mfma_f32_16x16x32_bf16 v[122:125], v[152:155], v[194:197], v[122:125]
	v_mfma_f32_16x16x32_bf16 v[114:117], v[144:147], v[220:223], v[114:117]
	v_mfma_f32_16x16x32_bf16 v[110:113], v[152:155], v[220:223], v[110:113]
	v_mfma_f32_16x16x32_bf16 v[98:101], v[144:147], v[228:231], v[98:101]
	v_mfma_f32_16x16x32_bf16 v[94:97], v[152:155], v[228:231], v[94:97]
	v_mfma_f32_16x16x32_bf16 v[82:85], v[144:147], v[236:239], v[82:85]
	v_mfma_f32_16x16x32_bf16 v[78:81], v[152:155], v[236:239], v[78:81]
	v_mfma_f32_16x16x32_bf16 v[118:121], v[156:159], v[190:193], v[118:121]
	v_mfma_f32_16x16x32_bf16 v[106:109], v[164:167], v[190:193], v[106:109]
	v_mfma_f32_16x16x32_bf16 v[102:105], v[156:159], v[212:215], v[102:105]
	v_mfma_f32_16x16x32_bf16 v[90:93], v[164:167], v[212:215], v[90:93]
	v_mfma_f32_16x16x32_bf16 v[86:89], v[156:159], v[224:227], v[86:89]
	v_mfma_f32_16x16x32_bf16 v[74:77], v[164:167], v[224:227], v[74:77]
	v_mfma_f32_16x16x32_bf16 v[70:73], v[156:159], v[232:235], v[70:73]
	v_mfma_f32_16x16x32_bf16 v[66:69], v[164:167], v[232:235], v[66:69]
	v_mfma_f32_16x16x32_bf16 v[118:121], v[160:163], v[194:197], v[118:121]
	v_mfma_f32_16x16x32_bf16 v[106:109], v[186:189], v[194:197], v[106:109]
	v_mfma_f32_16x16x32_bf16 v[102:105], v[160:163], v[220:223], v[102:105]
	v_mfma_f32_16x16x32_bf16 v[90:93], v[186:189], v[220:223], v[90:93]
	v_mfma_f32_16x16x32_bf16 v[86:89], v[160:163], v[228:231], v[86:89]
	v_mfma_f32_16x16x32_bf16 v[74:77], v[186:189], v[228:231], v[74:77]
	v_mfma_f32_16x16x32_bf16 v[70:73], v[160:163], v[236:239], v[70:73]
	v_mfma_f32_16x16x32_bf16 v[66:69], v[186:189], v[236:239], v[66:69]
	s_setprio 0
	s_barrier
	s_add_i32 s24, s58, s35
	v_lshl_add_u64 v[168:169], s[28:29], 0, v[32:33]
	s_mov_b32 m0, s24
	ds_read_b128 v[190:193], v143 offset:16384
	ds_read_b128 v[194:197], v143 offset:17408
	ds_read_b128 v[212:215], v143 offset:18432
	ds_read_b128 v[220:223], v143 offset:19456
	ds_read_b128 v[224:227], v143 offset:20480
	ds_read_b128 v[228:231], v143 offset:21504
	ds_read_b128 v[232:235], v143 offset:22528
	ds_read_b128 v[236:239], v143 offset:23552
	global_load_lds_dwordx4 v[168:169], off
	s_add_i32 m0, s24, 0x2000
	s_add_u32 s24, s28, 0x160000
	v_lshl_add_u64 v[216:217], s[28:29], 0, v[130:131]
	s_addc_u32 s25, s29, 0
	s_add_i32 s58, s59, s35
	global_load_lds_dwordx4 v[216:217], off
	v_lshl_add_u64 v[240:241], s[24:25], 0, v[32:33]
	s_mov_b32 m0, s58
	v_lshl_add_u64 v[242:243], s[30:31], 0, v[130:131]
	global_load_lds_dwordx4 v[240:241], off
	v_lshl_add_u64 v[240:241], s[24:25], 0, v[130:131]
	s_add_i32 m0, s58, 0x2000
	s_nop 0
	global_load_lds_dwordx4 v[240:241], off
	v_lshl_add_u64 v[240:241], s[30:31], 0, v[32:33]
	s_mov_b32 m0, s38
	s_nop 0
	global_load_lds_dwordx4 v[240:241], off
	s_mov_b32 m0, s39
	s_nop 0
	global_load_lds_dwordx4 v[242:243], off
	s_waitcnt vmcnt(8)
	s_waitcnt lgkmcnt(0)
	s_setprio 1
	s_barrier
; #define PG8_STAGE(bufoff, gbase, voff) do { _Pragma("unroll") for (int _i = 0; _i < 2; ++_i) \
;         __builtin_amdgcn_global_load_lds((const unsigned*)((const char*)(gbase) + (voff)[_i]), (PG8_LAS unsigned*)(lds + (bufoff) + ldsw + _i * 8192), 16, 0, 0); } while (0)
; #define PG8_LDA(dst, b, h) do { _Pragma("unroll") for (int m = 0; m < 4; ++m) _Pragma("unroll") for (int k = 0; k < 2; ++k) dst[m][k] = *(const PG8_LAS bf16x8*)(lds + PG8_SA(b, h) + aoff + m * 2048 + k * 1024); } while (0)
; #define PG8_LDB(dst, b, h) do { _Pragma("unroll") for (int n = 0; n < 2; ++n) _Pragma("unroll") for (int k = 0; k < 2; ++k) dst[n][k] = *(const PG8_LAS bf16x8*)(lds + PG8_SB(b, h) + boff + n * 2048 + k * 1024); } while (0)
; #define PG8_MMA(ai, bj, At, Bt) do { __builtin_amdgcn_s_setprio(1); _Pragma("unroll") for (int m = 0; m < 4; ++m) _Pragma("unroll") for (int n = 0; n < 2; ++n) _Pragma("unroll") for (int k = 0; k < 2; ++k) \
;         acc[ai][bj][m][n] = __builtin_amdgcn_mfma_f32_16x16x32_bf16(Bt[n][k], At[m][k], acc[ai][bj][m][n], 0, 0, 0); __builtin_amdgcn_s_setprio(0); } while (0)
; #define PG8_WAIT_V(n) asm volatile("s_waitcnt vmcnt(" #n ")" ::: "memory")
; #define PG8_WAIT_L(n) asm volatile("s_waitcnt lgkmcnt(" #n ")" ::: "memory")
; #define PG8_BAR __builtin_amdgcn_s_barrier()
; #define PG8_SCHED __builtin_amdgcn_sched_barrier(0)
; template <class Epi, class Sched, bool ALIGN_EPI = false, bool SP2 = false>
; __device__ __forceinline__ void gemm_phase(PG8_LAS unsigned char* lds, const Gemm g, const Sched& S, const Epi& E, int tid_in) {
;     ...
;             PG8_WAIT_V(8); PG8_WAIT_L(0); PG8_BAR; PG8_MMA(1, 0, At, B0); PG8_MMA(1, 1, At, B1); PG8_BAR; PG8_SCHED;
;             PG8_LDB(B0, 1, 0); PG8_LDB(B1, 1, 1); PG8_SCHED; PG8_LDA(At, 1, 0); PG8_STAGE(PG8_SA(0, 1), a2 + hstep, voffA);
;             PG8_WAIT_V(8); PG8_WAIT_L(0); PG8_BAR; PG8_MMA(0, 0, At, B0); PG8_MMA(0, 1, At, B1); PG8_BAR; PG8_SCHED;
	v_mfma_f32_16x16x32_bf16 v[62:65], v[136:139], v[190:193], v[62:65]
	v_mfma_f32_16x16x32_bf16 v[58:61], v[148:151], v[190:193], v[58:61]
	v_mfma_f32_16x16x32_bf16 v[50:53], v[136:139], v[212:215], v[50:53]
	v_mfma_f32_16x16x32_bf16 v[46:49], v[148:151], v[212:215], v[46:49]
	v_mfma_f32_16x16x32_bf16 v[34:37], v[136:139], v[224:227], v[34:37]
	v_mfma_f32_16x16x32_bf16 v[28:31], v[148:151], v[224:227], v[28:31]
	v_mfma_f32_16x16x32_bf16 v[16:19], v[136:139], v[232:235], v[16:19]
	v_mfma_f32_16x16x32_bf16 v[12:15], v[148:151], v[232:235], v[12:15]
	v_mfma_f32_16x16x32_bf16 v[62:65], v[144:147], v[194:197], v[62:65]
	v_mfma_f32_16x16x32_bf16 v[58:61], v[152:155], v[194:197], v[58:61]
	v_mfma_f32_16x16x32_bf16 v[50:53], v[144:147], v[220:223], v[50:53]
	v_mfma_f32_16x16x32_bf16 v[46:49], v[152:155], v[220:223], v[46:49]
	v_mfma_f32_16x16x32_bf16 v[34:37], v[144:147], v[228:231], v[34:37]
	v_mfma_f32_16x16x32_bf16 v[28:31], v[152:155], v[228:231], v[28:31]
	v_mfma_f32_16x16x32_bf16 v[16:19], v[144:147], v[236:239], v[16:19]
	v_mfma_f32_16x16x32_bf16 v[12:15], v[152:155], v[236:239], v[12:15]
	v_mfma_f32_16x16x32_bf16 v[54:57], v[156:159], v[190:193], v[54:57]
	v_mfma_f32_16x16x32_bf16 v[42:45], v[164:167], v[190:193], v[42:45]
	v_mfma_f32_16x16x32_bf16 v[38:41], v[156:159], v[212:215], v[38:41]
	v_mfma_f32_16x16x32_bf16 v[24:27], v[164:167], v[212:215], v[24:27]
	v_mfma_f32_16x16x32_bf16 v[20:23], v[156:159], v[224:227], v[20:23]
	v_mfma_f32_16x16x32_bf16 v[8:11], v[164:167], v[224:227], v[8:11]
	v_mfma_f32_16x16x32_bf16 v[4:7], v[156:159], v[232:235], v[4:7]
	v_mfma_f32_16x16x32_bf16 v[0:3], v[164:167], v[232:235], v[0:3]
	v_mfma_f32_16x16x32_bf16 v[54:57], v[160:163], v[194:197], v[54:57]
	v_mfma_f32_16x16x32_bf16 v[42:45], v[186:189], v[194:197], v[42:45]
	v_mfma_f32_16x16x32_bf16 v[38:41], v[160:163], v[220:223], v[38:41]
	v_mfma_f32_16x16x32_bf16 v[24:27], v[186:189], v[220:223], v[24:27]
	v_mfma_f32_16x16x32_bf16 v[20:23], v[160:163], v[228:231], v[20:23]
	v_mfma_f32_16x16x32_bf16 v[8:11], v[186:189], v[228:231], v[8:11]
	v_mfma_f32_16x16x32_bf16 v[4:7], v[160:163], v[236:239], v[4:7]
	v_mfma_f32_16x16x32_bf16 v[0:3], v[186:189], v[236:239], v[0:3]
	s_setprio 0
	s_barrier
	s_add_i32 s58, 0, 0x18000
	s_add_i32 s59, 0, 0x1c000
	v_add_u32_e32 v152, s58, v141
	v_add_u32_e32 v170, s59, v141
	ds_read_b128 v[136:139], v152
	ds_read_b128 v[144:147], v152 offset:1024
	ds_read_b128 v[148:151], v152 offset:2048
	ds_read_b128 v[152:155], v152 offset:3072
	ds_read_b128 v[156:159], v170
	ds_read_b128 v[160:163], v170 offset:1024
	ds_read_b128 v[164:167], v170 offset:2048
	ds_read_b128 v[186:189], v170 offset:3072
	s_add_u32 s24, s30, 0x160000
	s_addc_u32 s25, s31, 0
	s_mov_b32 m0, s42
	v_lshl_add_u64 v[244:245], s[24:25], 0, v[32:33]
	ds_read_b128 v[190:193], v143 offset:32768
	ds_read_b128 v[194:197], v143 offset:33792
	ds_read_b128 v[212:215], v143 offset:34816
	ds_read_b128 v[220:223], v143 offset:35840
	ds_read_b128 v[224:227], v143 offset:36864
	ds_read_b128 v[228:231], v143 offset:37888
	ds_read_b128 v[232:235], v143 offset:38912
	ds_read_b128 v[236:239], v143 offset:39936
	global_load_lds_dwordx4 v[244:245], off
	v_lshl_add_u64 v[244:245], s[24:25], 0, v[130:131]
	s_mov_b32 m0, s43
	s_nop 0
	global_load_lds_dwordx4 v[244:245], off
	s_waitcnt vmcnt(8)
	s_waitcnt lgkmcnt(0)
	s_setprio 1
	s_barrier
	v_mfma_f32_16x16x32_bf16 v[126:129], v[136:139], v[190:193], v[126:129]
	v_mfma_f32_16x16x32_bf16 v[122:125], v[148:151], v[190:193], v[122:125]
	v_mfma_f32_16x16x32_bf16 v[114:117], v[136:139], v[212:215], v[114:117]
	v_mfma_f32_16x16x32_bf16 v[110:113], v[148:151], v[212:215], v[110:113]
	v_mfma_f32_16x16x32_bf16 v[98:101], v[136:139], v[224:227], v[98:101]
	v_mfma_f32_16x16x32_bf16 v[94:97], v[148:151], v[224:227], v[94:97]
	v_mfma_f32_16x16x32_bf16 v[82:85], v[136:139], v[232:235], v[82:85]
	v_mfma_f32_16x16x32_bf16 v[78:81], v[148:151], v[232:235], v[78:81]
	v_mfma_f32_16x16x32_bf16 v[126:129], v[144:147], v[194:197], v[126:129]
	v_mfma_f32_16x16x32_bf16 v[122:125], v[152:155], v[194:197], v[122:125]
	v_mfma_f32_16x16x32_bf16 v[114:117], v[144:147], v[220:223], v[114:117]
	v_mfma_f32_16x16x32_bf16 v[110:113], v[152:155], v[220:223], v[110:113]
	v_mfma_f32_16x16x32_bf16 v[98:101], v[144:147], v[228:231], v[98:101]
	v_mfma_f32_16x16x32_bf16 v[94:97], v[152:155], v[228:231], v[94:97]
	v_mfma_f32_16x16x32_bf16 v[82:85], v[144:147], v[236:239], v[82:85]
	v_mfma_f32_16x16x32_bf16 v[78:81], v[152:155], v[236:239], v[78:81]
	v_mfma_f32_16x16x32_bf16 v[118:121], v[156:159], v[190:193], v[118:121]
	v_mfma_f32_16x16x32_bf16 v[106:109], v[164:167], v[190:193], v[106:109]
	v_mfma_f32_16x16x32_bf16 v[102:105], v[156:159], v[212:215], v[102:105]
	v_mfma_f32_16x16x32_bf16 v[90:93], v[164:167], v[212:215], v[90:93]
	v_mfma_f32_16x16x32_bf16 v[86:89], v[156:159], v[224:227], v[86:89]
	v_mfma_f32_16x16x32_bf16 v[74:77], v[164:167], v[224:227], v[74:77]
	v_mfma_f32_16x16x32_bf16 v[70:73], v[156:159], v[232:235], v[70:73]
	v_mfma_f32_16x16x32_bf16 v[66:69], v[164:167], v[232:235], v[66:69]
	v_mfma_f32_16x16x32_bf16 v[118:121], v[160:163], v[194:197], v[118:121]
	v_mfma_f32_16x16x32_bf16 v[106:109], v[186:189], v[194:197], v[106:109]
	v_mfma_f32_16x16x32_bf16 v[102:105], v[160:163], v[220:223], v[102:105]
	v_mfma_f32_16x16x32_bf16 v[90:93], v[186:189], v[220:223], v[90:93]
	v_mfma_f32_16x16x32_bf16 v[86:89], v[160:163], v[228:231], v[86:89]
	v_mfma_f32_16x16x32_bf16 v[74:77], v[186:189], v[228:231], v[74:77]
	v_mfma_f32_16x16x32_bf16 v[70:73], v[160:163], v[236:239], v[70:73]
	v_mfma_f32_16x16x32_bf16 v[66:69], v[186:189], v[236:239], v[66:69]
	s_setprio 0
	s_barrier
; #define PG8_STAGE(bufoff, gbase, voff) do { _Pragma("unroll") for (int _i = 0; _i < 2; ++_i) \
;         __builtin_amdgcn_global_load_lds((const unsigned*)((const char*)(gbase) + (voff)[_i]), (PG8_LAS unsigned*)(lds + (bufoff) + ldsw + _i * 8192), 16, 0, 0); } while (0)
; #define PG8_LDA(dst, b, h) do { _Pragma("unroll") for (int m = 0; m < 4; ++m) _Pragma("unroll") for (int k = 0; k < 2; ++k) dst[m][k] = *(const PG8_LAS bf16x8*)(lds + PG8_SA(b, h) + aoff + m * 2048 + k * 1024); } while (0)
; #define PG8_MMA(ai, bj, At, Bt) do { __builtin_amdgcn_s_setprio(1); _Pragma("unroll") for (int m = 0; m < 4; ++m) _Pragma("unroll") for (int n = 0; n < 2; ++n) _Pragma("unroll") for (int k = 0; k < 2; ++k) \
;         acc[ai][bj][m][n] = __builtin_amdgcn_mfma_f32_16x16x32_bf16(Bt[n][k], At[m][k], acc[ai][bj][m][n], 0, 0, 0); __builtin_amdgcn_s_setprio(0); } while (0)
; #define PG8_WAIT_V(n) asm volatile("s_waitcnt vmcnt(" #n ")" ::: "memory")
; #define PG8_WAIT_L(n) asm volatile("s_waitcnt lgkmcnt(" #n ")" ::: "memory")
; #define PG8_BAR __builtin_amdgcn_s_barrier()
; #define PG8_SCHED __builtin_amdgcn_sched_barrier(0)
; template <class Epi, class Sched, bool ALIGN_EPI = false, bool SP2 = false>
; __device__ __forceinline__ void gemm_phase(PG8_LAS unsigned char* lds, const Gemm g, const Sched& S, const Epi& E, int tid_in) {
;     ...
;         for (int t = 0; t < nt; t += 2) {
;     ...
;             PG8_LDA(At, 1, 1); PG8_STAGE(PG8_SB(1, 0), b3, voffB); PG8_STAGE(PG8_SB(1, 1), b3 + hstep, voffB); PG8_STAGE(PG8_SA(1, 0), a3, voffA);
;             PG8_WAIT_V(8); PG8_WAIT_L(0); PG8_BAR; PG8_MMA(1, 0, At, B0); PG8_MMA(1, 1, At, B1); PG8_BAR; PG8_SCHED;
	s_add_i32 s24, s58, s35
	v_lshl_add_u64 v[168:169], v[168:169], 0, s[74:75]
	s_mov_b32 m0, s24
	ds_read_b128 v[190:193], v143 offset:49152
	ds_read_b128 v[194:197], v143 offset:50176
	ds_read_b128 v[212:215], v143 offset:51200
	ds_read_b128 v[220:223], v143 offset:52224
	ds_read_b128 v[224:227], v143 offset:53248
	ds_read_b128 v[228:231], v143 offset:54272
	ds_read_b128 v[232:235], v143 offset:55296
	ds_read_b128 v[236:239], v143 offset:56320
	global_load_lds_dwordx4 v[168:169], off
	s_add_i32 m0, s24, 0x2000
	s_add_u32 s24, s28, 0x160080
	v_lshl_add_u64 v[168:169], v[216:217], 0, s[74:75]
	s_addc_u32 s25, s29, 0
	s_add_i32 s28, s59, s35
	global_load_lds_dwordx4 v[168:169], off
	v_lshl_add_u64 v[168:169], s[24:25], 0, v[32:33]
	s_mov_b32 m0, s28
	s_nop 0
	global_load_lds_dwordx4 v[168:169], off
	v_lshl_add_u64 v[168:169], s[24:25], 0, v[130:131]
	s_add_i32 m0, s28, 0x2000
	s_nop 0
	global_load_lds_dwordx4 v[168:169], off
	v_lshl_add_u64 v[168:169], v[240:241], 0, s[74:75]
	s_mov_b32 m0, s48
	s_nop 0
	global_load_lds_dwordx4 v[168:169], off
	v_lshl_add_u64 v[168:169], v[242:243], 0, s[74:75]
	s_mov_b32 m0, s49
	s_nop 0
	global_load_lds_dwordx4 v[168:169], off
	s_waitcnt vmcnt(8)
	s_waitcnt lgkmcnt(0)
	s_setprio 1
	s_barrier
	v_mfma_f32_16x16x32_bf16 v[62:65], v[136:139], v[190:193], v[62:65]
	v_mfma_f32_16x16x32_bf16 v[58:61], v[148:151], v[190:193], v[58:61]
	v_mfma_f32_16x16x32_bf16 v[50:53], v[136:139], v[212:215], v[50:53]
	v_mfma_f32_16x16x32_bf16 v[46:49], v[148:151], v[212:215], v[46:49]
	v_mfma_f32_16x16x32_bf16 v[34:37], v[136:139], v[224:227], v[34:37]
	v_mfma_f32_16x16x32_bf16 v[28:31], v[148:151], v[224:227], v[28:31]
	v_mfma_f32_16x16x32_bf16 v[16:19], v[136:139], v[232:235], v[16:19]
	v_mfma_f32_16x16x32_bf16 v[12:15], v[148:151], v[232:235], v[12:15]
	v_mfma_f32_16x16x32_bf16 v[62:65], v[144:147], v[194:197], v[62:65]
	v_mfma_f32_16x16x32_bf16 v[58:61], v[152:155], v[194:197], v[58:61]
	v_mfma_f32_16x16x32_bf16 v[50:53], v[144:147], v[220:223], v[50:53]
	v_mfma_f32_16x16x32_bf16 v[46:49], v[152:155], v[220:223], v[46:49]
	v_mfma_f32_16x16x32_bf16 v[34:37], v[144:147], v[228:231], v[34:37]
	v_mfma_f32_16x16x32_bf16 v[28:31], v[152:155], v[228:231], v[28:31]
	v_mfma_f32_16x16x32_bf16 v[16:19], v[144:147], v[236:239], v[16:19]
	v_mfma_f32_16x16x32_bf16 v[12:15], v[152:155], v[236:239], v[12:15]
	v_mfma_f32_16x16x32_bf16 v[54:57], v[156:159], v[190:193], v[54:57]
	v_mfma_f32_16x16x32_bf16 v[42:45], v[164:167], v[190:193], v[42:45]
	v_mfma_f32_16x16x32_bf16 v[38:41], v[156:159], v[212:215], v[38:41]
	v_mfma_f32_16x16x32_bf16 v[24:27], v[164:167], v[212:215], v[24:27]
	v_mfma_f32_16x16x32_bf16 v[20:23], v[156:159], v[224:227], v[20:23]
	v_mfma_f32_16x16x32_bf16 v[8:11], v[164:167], v[224:227], v[8:11]
	v_mfma_f32_16x16x32_bf16 v[4:7], v[156:159], v[232:235], v[4:7]
	v_mfma_f32_16x16x32_bf16 v[0:3], v[164:167], v[232:235], v[0:3]
	v_mfma_f32_16x16x32_bf16 v[54:57], v[160:163], v[194:197], v[54:57]
	v_mfma_f32_16x16x32_bf16 v[42:45], v[186:189], v[194:197], v[42:45]
	v_mfma_f32_16x16x32_bf16 v[38:41], v[160:163], v[220:223], v[38:41]
	v_mfma_f32_16x16x32_bf16 v[24:27], v[186:189], v[220:223], v[24:27]
	v_mfma_f32_16x16x32_bf16 v[20:23], v[160:163], v[228:231], v[20:23]
	v_mfma_f32_16x16x32_bf16 v[8:11], v[186:189], v[228:231], v[8:11]
	v_mfma_f32_16x16x32_bf16 v[4:7], v[160:163], v[236:239], v[4:7]
	v_mfma_f32_16x16x32_bf16 v[0:3], v[186:189], v[236:239], v[0:3]
	s_setprio 0
	s_barrier
	s_add_i32 s57, s57, 2
	s_add_u32 s45, s45, 0x100
	s_addc_u32 s47, s47, 0
	s_cmpk_gt_u32 s57, 0x55
	s_mov_b64 s[24:25], s[26:27]
	s_cbranch_scc0 .LBB0_625
	s_and_b64 vcc, exec, s[20:21]
	s_cbranch_vccz .LBB0_628
	s_barrier
